# write-through (sc0 sc1) epilogue stores in the single-unit GEMM phases (merge, w_out, down) so the barrier's L2 writeback has little left to flush
# baseline (speedup 1.0000x reference)
; __device__ __forceinline__ unsigned pkh(float lo, float hi) { f32v2_t v; v.x = lo; v.y = hi; return __builtin_bit_cast(unsigned, __builtin_convertvector(v, bf16v2_t)); }
; __device__ __forceinline__ float bf_lo(unsigned w) { return __uint_as_float(w << 16); }
; __device__ __forceinline__ float bf_hi(unsigned w) { return __uint_as_float(w & 0xffff0000u); }
; __device__ __forceinline__ float sigmoidf_(float x) { return 1.0f / (1.0f + __expf(-x)); }
;     template <int MODE> __device__ __forceinline__ void run(const pg8::f32x4 (&acc)[2][2][4][2], const pg8::Unit& u, int wr, int wc, int fr, int fq) const {
;     ...
;                 for (int q = 0; q < 4; ++q) { const int m = 2 * mp + (q >> 1), bj = q & 1; const int row = u.pm * 256 + ai * 128 + wr * 64 + m * 16 + fr, col = u.pn * 256 + bj * 128 + wc * 32 + 8 * fq;
;                     const pg8::f32x4 t0 = acc[ai][bj][m][0], t1 = acc[ai][bj][m][1];
;                     float v[8] = {t0[0], t0[1], t0[2], t0[3], t1[0], t1[1], t1[2], t1[3]};
;                     if constexpr (MODE == 5) {
; #pragma unroll
;                         for (int e = 0; e < 8; ++e) { const float r = fmaxf(v[e], 0.f); v[e] = r * r; }
;                     }
;                     if constexpr (MODE == 6) { const u32x4 g = gpre[q];
;                         v[0] *= sigmoidf_(bf_lo(g.x)); v[1] *= sigmoidf_(bf_hi(g.x)); v[2] *= sigmoidf_(bf_lo(g.y)); v[3] *= sigmoidf_(bf_hi(g.y));
;                         v[4] *= sigmoidf_(bf_lo(g.z)); v[5] *= sigmoidf_(bf_hi(g.z)); v[6] *= sigmoidf_(bf_lo(g.w)); v[7] *= sigmoidf_(bf_hi(g.w)); }
;                     u32x4 w; w.x = pkh(v[0], v[1]); w.y = pkh(v[2], v[3]); w.z = pkh(v[4], v[5]); w.w = pkh(v[6], v[7]);
;                     *(u32x4*)(ob + (size_t)row * LDC + col) = w; }
.LBB0_65:
	s_and_b64 vcc, exec, s[34:35]
	s_cbranch_vccz .LBB0_67
	v_mov_b32_e32 v0, v210
	s_lshl_b32 s2, s53, 8
	v_and_or_b32 v2, v0, 15, s49
	v_lshrrev_b32_e32 v0, 1, v0
	v_lshl_add_u32 v2, s54, 8, v2
	v_and_or_b32 v0, v0, 24, s2
	v_or_b32_e32 v136, s50, v0
	v_ashrrev_i32_e32 v3, 31, v2
	v_lshlrev_b64 v[138:139], 12, v[2:3]
	v_ashrrev_i32_e32 v137, 31, v136
	v_lshl_add_u64 v[138:139], s[10:11], 0, v[138:139]
	v_lshlrev_b64 v[136:137], 1, v[136:137]
	v_cvt_pk_bf16_f32 v132, v116, v117
	v_cvt_pk_bf16_f32 v133, v118, v119
	v_cvt_pk_bf16_f32 v134, v120, v121
	v_cvt_pk_bf16_f32 v135, v122, v123
	v_lshl_add_u64 v[138:139], v[138:139], 0, v[136:137]
	global_store_dwordx4 v[138:139], v[132:135], off sc0 sc1
	s_nop 1
	v_cvt_pk_bf16_f32 v132, v124, v125
	v_cvt_pk_bf16_f32 v133, v126, v127
	v_cvt_pk_bf16_f32 v134, v128, v129
	v_cvt_pk_bf16_f32 v135, v130, v131
	global_store_dwordx4 v[138:139], v[132:135], off offset:256 sc0 sc1
	v_or_b32_e32 v138, 16, v2
	v_ashrrev_i32_e32 v139, 31, v138
	v_lshlrev_b64 v[138:139], 12, v[138:139]
	v_lshl_add_u64 v[138:139], s[10:11], 0, v[138:139]
	v_cvt_pk_bf16_f32 v132, v100, v101
	v_cvt_pk_bf16_f32 v133, v102, v103
	v_cvt_pk_bf16_f32 v134, v104, v105
	v_cvt_pk_bf16_f32 v135, v106, v107
	v_lshl_add_u64 v[138:139], v[138:139], 0, v[136:137]
	global_store_dwordx4 v[138:139], v[132:135], off sc0 sc1
	s_nop 1
	v_cvt_pk_bf16_f32 v132, v108, v109
	v_cvt_pk_bf16_f32 v133, v110, v111
	v_cvt_pk_bf16_f32 v134, v112, v113
	v_cvt_pk_bf16_f32 v135, v114, v115
	global_store_dwordx4 v[138:139], v[132:135], off offset:256 sc0 sc1
	v_or_b32_e32 v138, 32, v2
	v_ashrrev_i32_e32 v139, 31, v138
	v_lshlrev_b64 v[138:139], 12, v[138:139]
	v_lshl_add_u64 v[138:139], s[10:11], 0, v[138:139]
	v_cvt_pk_bf16_f32 v132, v76, v77
	v_cvt_pk_bf16_f32 v133, v78, v79
	v_cvt_pk_bf16_f32 v134, v80, v81
	v_cvt_pk_bf16_f32 v135, v82, v83
	v_lshl_add_u64 v[138:139], v[138:139], 0, v[136:137]
	global_store_dwordx4 v[138:139], v[132:135], off sc0 sc1
	s_nop 1
	v_cvt_pk_bf16_f32 v132, v92, v93
	v_cvt_pk_bf16_f32 v133, v94, v95
	v_cvt_pk_bf16_f32 v134, v96, v97
	v_cvt_pk_bf16_f32 v135, v98, v99
	global_store_dwordx4 v[138:139], v[132:135], off offset:256 sc0 sc1
	v_or_b32_e32 v138, 48, v2
	v_ashrrev_i32_e32 v139, 31, v138
	v_lshlrev_b64 v[138:139], 12, v[138:139]
	v_lshl_add_u64 v[138:139], s[10:11], 0, v[138:139]
	v_cvt_pk_bf16_f32 v132, v44, v45
	v_cvt_pk_bf16_f32 v133, v46, v47
	v_cvt_pk_bf16_f32 v134, v48, v49
	v_cvt_pk_bf16_f32 v135, v50, v51
	v_lshl_add_u64 v[138:139], v[138:139], 0, v[136:137]
	global_store_dwordx4 v[138:139], v[132:135], off sc0 sc1
	s_nop 1
	v_cvt_pk_bf16_f32 v132, v68, v69
	v_cvt_pk_bf16_f32 v133, v70, v71
	v_cvt_pk_bf16_f32 v134, v72, v73
	v_cvt_pk_bf16_f32 v135, v74, v75
	global_store_dwordx4 v[138:139], v[132:135], off offset:256 sc0 sc1
	v_add_u32_e32 v138, 0x80, v2
	v_ashrrev_i32_e32 v139, 31, v138
	v_lshlrev_b64 v[138:139], 12, v[138:139]
	v_lshl_add_u64 v[138:139], s[10:11], 0, v[138:139]
	v_cvt_pk_bf16_f32 v132, v60, v61
	v_cvt_pk_bf16_f32 v133, v62, v63
	v_cvt_pk_bf16_f32 v134, v64, v65
	v_cvt_pk_bf16_f32 v135, v66, v67
	v_lshl_add_u64 v[138:139], v[138:139], 0, v[136:137]
	global_store_dwordx4 v[138:139], v[132:135], off sc0 sc1
	s_nop 1
	v_cvt_pk_bf16_f32 v132, v84, v85
	v_cvt_pk_bf16_f32 v133, v86, v87
	v_cvt_pk_bf16_f32 v134, v88, v89
	v_cvt_pk_bf16_f32 v135, v90, v91
	global_store_dwordx4 v[138:139], v[132:135], off offset:256 sc0 sc1
	v_add_u32_e32 v138, 0x90, v2
	v_ashrrev_i32_e32 v139, 31, v138
	v_lshlrev_b64 v[138:139], 12, v[138:139]
	v_lshl_add_u64 v[138:139], s[10:11], 0, v[138:139]
	v_cvt_pk_bf16_f32 v132, v36, v37
	v_cvt_pk_bf16_f32 v133, v38, v39
	v_cvt_pk_bf16_f32 v134, v40, v41
	v_cvt_pk_bf16_f32 v135, v42, v43
	v_lshl_add_u64 v[138:139], v[138:139], 0, v[136:137]
	global_store_dwordx4 v[138:139], v[132:135], off sc0 sc1
	s_nop 1
	v_cvt_pk_bf16_f32 v132, v52, v53
	v_cvt_pk_bf16_f32 v133, v54, v55
	v_cvt_pk_bf16_f32 v134, v56, v57
	v_cvt_pk_bf16_f32 v135, v58, v59
	global_store_dwordx4 v[138:139], v[132:135], off offset:256 sc0 sc1
	v_add_u32_e32 v138, 0xa0, v2
	v_ashrrev_i32_e32 v139, 31, v138
	v_lshlrev_b64 v[138:139], 12, v[138:139]
	v_add_u32_e32 v2, 0xb0, v2
	v_lshl_add_u64 v[138:139], s[10:11], 0, v[138:139]
	v_ashrrev_i32_e32 v3, 31, v2
	v_cvt_pk_bf16_f32 v132, v20, v21
	v_cvt_pk_bf16_f32 v133, v22, v23
	v_cvt_pk_bf16_f32 v134, v24, v25
	v_cvt_pk_bf16_f32 v135, v26, v27
	v_lshl_add_u64 v[138:139], v[138:139], 0, v[136:137]
	v_lshlrev_b64 v[2:3], 12, v[2:3]
	global_store_dwordx4 v[138:139], v[132:135], off sc0 sc1
	v_lshl_add_u64 v[2:3], s[10:11], 0, v[2:3]
	v_lshl_add_u64 v[2:3], v[2:3], 0, v[136:137]
	v_cvt_pk_bf16_f32 v132, v28, v29
	v_cvt_pk_bf16_f32 v133, v30, v31
	v_cvt_pk_bf16_f32 v134, v32, v33
	v_cvt_pk_bf16_f32 v135, v34, v35
	global_store_dwordx4 v[138:139], v[132:135], off offset:256 sc0 sc1
	s_nop 1
	v_cvt_pk_bf16_f32 v132, v4, v5
	v_cvt_pk_bf16_f32 v133, v6, v7
	v_cvt_pk_bf16_f32 v134, v8, v9
	v_cvt_pk_bf16_f32 v135, v10, v11
	global_store_dwordx4 v[2:3], v[132:135], off sc0 sc1
	s_nop 1
	v_cvt_pk_bf16_f32 v132, v12, v13
	v_cvt_pk_bf16_f32 v133, v14, v15
	v_cvt_pk_bf16_f32 v134, v16, v17
	v_cvt_pk_bf16_f32 v135, v18, v19
	global_store_dwordx4 v[2:3], v[132:135], off offset:256 sc0 sc1

; __device__ __forceinline__ float bf_lo(unsigned w) { return __uint_as_float(w << 16); }
; __device__ __forceinline__ float bf_hi(unsigned w) { return __uint_as_float(w & 0xffff0000u); }
; __device__ __forceinline__ float sigmoidf_(float x) { return 1.0f / (1.0f + __expf(-x)); }
;     template <int MODE> __device__ __forceinline__ void run(const pg8::f32x4 (&acc)[2][2][4][2], const pg8::Unit& u, int wr, int wc, int fr, int fq) const {
;     ...
;                 if constexpr (MODE == 6) {
; #pragma unroll
;                     for (int q = 0; q < 4; ++q) { const int m = 2 * mp + (q >> 1), bj = q & 1; const int row = u.pm * 256 + ai * 128 + wr * 64 + m * 16 + fr, col = u.pn * 256 + bj * 128 + wc * 32 + 8 * fq;
;                         gpre[q] = *(const u32x4*)(proj + (size_t)row * NP + OFF_MG + 2 * DM + col); }
;                 }
; #pragma unroll
;                 for (int q = 0; q < 4; ++q) { const int m = 2 * mp + (q >> 1), bj = q & 1; const int row = u.pm * 256 + ai * 128 + wr * 64 + m * 16 + fr, col = u.pn * 256 + bj * 128 + wc * 32 + 8 * fq;
;                     const pg8::f32x4 t0 = acc[ai][bj][m][0], t1 = acc[ai][bj][m][1];
;                     float v[8] = {t0[0], t0[1], t0[2], t0[3], t1[0], t1[1], t1[2], t1[3]};
;                     if constexpr (MODE == 5) {
; #pragma unroll
;                         for (int e = 0; e < 8; ++e) { const float r = fmaxf(v[e], 0.f); v[e] = r * r; }
;                     }
;                     if constexpr (MODE == 6) { const u32x4 g = gpre[q];
;                         v[0] *= sigmoidf_(bf_lo(g.x)); v[1] *= sigmoidf_(bf_hi(g.x)); v[2] *= sigmoidf_(bf_lo(g.y)); v[3] *= sigmoidf_(bf_hi(g.y));
;                         v[4] *= sigmoidf_(bf_lo(g.z)); v[5] *= sigmoidf_(bf_hi(g.z)); v[6] *= sigmoidf_(bf_lo(g.w)); v[7] *= sigmoidf_(bf_hi(g.w)); }
.LBB0_69:
	v_mov_b32_e32 v0, v210
	s_lshl_b32 s2, s53, 8
	v_and_or_b32 v2, v0, 15, s49
	v_lshrrev_b32_e32 v0, 1, v0
	v_and_or_b32 v0, v0, 24, s2
	v_lshl_add_u32 v148, s54, 8, v2
	v_or_b32_e32 v132, s50, v0
	v_mov_b64_e32 v[150:151], s[6:7]
	v_mad_i64_i32 v[2:3], s[28:29], v148, s76, v[150:151]
	s_mov_b64 s[30:31], 0x6a60
	v_ashrrev_i32_e32 v133, 31, v132
	v_lshl_add_u64 v[134:135], v[2:3], 0, s[30:31]
	v_lshlrev_b64 v[2:3], 1, v[132:133]
	v_lshl_add_u64 v[136:137], v[134:135], 0, v[2:3]
	global_load_dwordx4 v[144:147], v[136:137], off
	v_or_b32_e32 v132, 0x80, v132
	v_ashrrev_i32_e32 v133, 31, v132
	v_lshlrev_b64 v[152:153], 1, v[132:133]
	v_lshl_add_u64 v[132:133], v[134:135], 0, v[152:153]
	global_load_dwordx4 v[140:143], v[132:133], off
	v_ashrrev_i32_e32 v149, 31, v148
	v_or_b32_e32 v154, 16, v148
	v_mad_i64_i32 v[132:133], s[28:29], v154, s76, v[150:151]
	v_lshl_add_u64 v[132:133], v[132:133], 0, s[30:31]
	v_lshl_add_u64 v[134:135], v[132:133], 0, v[2:3]
	v_lshl_add_u64 v[132:133], v[132:133], 0, v[152:153]
	global_load_dwordx4 v[136:139], v[134:135], off
	v_ashrrev_i32_e32 v155, 31, v154
	global_load_dwordx4 v[132:135], v[132:133], off
	s_waitcnt vmcnt(0)
	v_lshlrev_b32_e32 v0, 16, v144
	v_mul_f32_e32 v0, 0xbfb8aa3b, v0
	v_exp_f32_e32 v156, v0
	v_and_b32_e32 v0, 0xffff0000, v144
	v_mul_f32_e32 v0, 0xbfb8aa3b, v0
	v_exp_f32_e32 v157, v0
	s_nop 0
	v_pk_add_f32 v[156:157], v[156:157], 1.0 op_sel_hi:[1,0]
	s_nop 0
	v_div_scale_f32 v0, s[28:29], v157, v157, 1.0
	v_rcp_f32_e32 v144, v0
	s_nop 0
	v_fma_f32 v158, -v0, v144, 1.0
	v_fmac_f32_e32 v144, v158, v144
	v_div_scale_f32 v158, vcc, 1.0, v157, 1.0
	v_mul_f32_e32 v159, v158, v144
	v_fma_f32 v160, -v0, v159, v158
	v_fmac_f32_e32 v159, v160, v144
	v_fma_f32 v0, -v0, v159, v158
	v_div_fmas_f32 v0, v0, v144, v159
	v_div_fixup_f32 v157, v0, v157, 1.0
	v_div_scale_f32 v0, s[28:29], v156, v156, 1.0
	v_rcp_f32_e32 v144, v0
	s_nop 0
	v_fma_f32 v158, -v0, v144, 1.0
	v_fmac_f32_e32 v144, v158, v144
	v_div_scale_f32 v158, vcc, 1.0, v156, 1.0
	v_mul_f32_e32 v159, v158, v144
	v_fma_f32 v160, -v0, v159, v158
	v_fmac_f32_e32 v159, v160, v144
	v_fma_f32 v0, -v0, v159, v158
	v_div_fmas_f32 v0, v0, v144, v159
	v_div_fixup_f32 v156, v0, v156, 1.0
	v_lshlrev_b32_e32 v0, 16, v145
	v_mul_f32_e32 v0, 0xbfb8aa3b, v0
	v_exp_f32_e32 v144, v0
	v_and_b32_e32 v0, 0xffff0000, v145
	v_mul_f32_e32 v0, 0xbfb8aa3b, v0
	v_exp_f32_e32 v145, v0
	v_pk_mul_f32 v[156:157], v[116:117], v[156:157]
	v_pk_add_f32 v[144:145], v[144:145], 1.0 op_sel_hi:[1,0]
	s_nop 0
	v_div_scale_f32 v0, s[28:29], v145, v145, 1.0
	v_rcp_f32_e32 v158, v0
	v_cvt_pk_bf16_f32 v156, v156, v157
	v_fma_f32 v159, -v0, v158, 1.0
	v_fmac_f32_e32 v158, v159, v158
	v_div_scale_f32 v159, vcc, 1.0, v145, 1.0
	v_mul_f32_e32 v160, v159, v158
	v_fma_f32 v161, -v0, v160, v159
	v_fmac_f32_e32 v160, v161, v158
	v_fma_f32 v0, -v0, v160, v159
	v_div_fmas_f32 v0, v0, v158, v160
	v_div_fixup_f32 v145, v0, v145, 1.0
	v_div_scale_f32 v0, s[28:29], v144, v144, 1.0
	v_rcp_f32_e32 v158, v0
	s_nop 0
	v_fma_f32 v159, -v0, v158, 1.0
	v_fmac_f32_e32 v158, v159, v158
	v_div_scale_f32 v159, vcc, 1.0, v144, 1.0
	v_mul_f32_e32 v160, v159, v158
	v_fma_f32 v161, -v0, v160, v159
	v_fmac_f32_e32 v160, v161, v158
	v_fma_f32 v0, -v0, v160, v159
	v_div_fmas_f32 v0, v0, v158, v160
	v_div_fixup_f32 v144, v0, v144, 1.0
	v_lshlrev_b32_e32 v0, 16, v146
	v_mul_f32_e32 v0, 0xbfb8aa3b, v0
	v_exp_f32_e32 v158, v0
	v_and_b32_e32 v0, 0xffff0000, v146
	v_mul_f32_e32 v0, 0xbfb8aa3b, v0
	v_exp_f32_e32 v159, v0
	v_pk_mul_f32 v[144:145], v[118:119], v[144:145]
	v_pk_add_f32 v[158:159], v[158:159], 1.0 op_sel_hi:[1,0]
	s_nop 0
	v_div_scale_f32 v0, s[28:29], v159, v159, 1.0
	v_rcp_f32_e32 v146, v0
	v_cvt_pk_bf16_f32 v157, v144, v145
	v_lshlrev_b64 v[144:145], 12, v[148:149]
	v_lshl_add_u64 v[144:145], s[10:11], 0, v[144:145]
	v_fma_f32 v160, -v0, v146, 1.0
	v_fmac_f32_e32 v146, v160, v146
	v_div_scale_f32 v160, vcc, 1.0, v159, 1.0
	v_mul_f32_e32 v161, v160, v146
	v_fma_f32 v162, -v0, v161, v160
	v_fmac_f32_e32 v161, v162, v146
	v_fma_f32 v0, -v0, v161, v160
	v_div_fmas_f32 v0, v0, v146, v161
	v_div_fixup_f32 v159, v0, v159, 1.0
	v_div_scale_f32 v0, s[28:29], v158, v158, 1.0
	v_rcp_f32_e32 v146, v0
	v_lshl_add_u64 v[144:145], v[144:145], 0, v[2:3]
	v_fma_f32 v160, -v0, v146, 1.0
	v_fmac_f32_e32 v146, v160, v146
	v_div_scale_f32 v160, vcc, 1.0, v158, 1.0
	v_mul_f32_e32 v161, v160, v146
	v_fma_f32 v162, -v0, v161, v160
	v_fmac_f32_e32 v161, v162, v146
	v_fma_f32 v0, -v0, v161, v160
	v_div_fmas_f32 v0, v0, v146, v161
	v_div_fixup_f32 v158, v0, v158, 1.0
	v_lshlrev_b32_e32 v0, 16, v147
	v_mul_f32_e32 v0, 0xbfb8aa3b, v0
	v_exp_f32_e32 v146, v0
	v_and_b32_e32 v0, 0xffff0000, v147
	v_mul_f32_e32 v0, 0xbfb8aa3b, v0
	v_exp_f32_e32 v147, v0
	v_pk_mul_f32 v[158:159], v[120:121], v[158:159]
	v_pk_add_f32 v[146:147], v[146:147], 1.0 op_sel_hi:[1,0]
	s_nop 0
	v_div_scale_f32 v0, s[28:29], v147, v147, 1.0
	v_rcp_f32_e32 v160, v0
	v_cvt_pk_bf16_f32 v158, v158, v159
	v_fma_f32 v161, -v0, v160, 1.0
	v_fmac_f32_e32 v160, v161, v160
	v_div_scale_f32 v161, vcc, 1.0, v147, 1.0
	v_mul_f32_e32 v162, v161, v160
	v_fma_f32 v163, -v0, v162, v161
	v_fmac_f32_e32 v162, v163, v160
	v_fma_f32 v0, -v0, v162, v161
	v_div_fmas_f32 v0, v0, v160, v162
	v_div_fixup_f32 v147, v0, v147, 1.0
	v_div_scale_f32 v0, s[28:29], v146, v146, 1.0
	v_rcp_f32_e32 v160, v0
	s_nop 0
	v_fma_f32 v161, -v0, v160, 1.0
	v_fmac_f32_e32 v160, v161, v160
	v_div_scale_f32 v161, vcc, 1.0, v146, 1.0
	v_mul_f32_e32 v162, v161, v160
	v_fma_f32 v163, -v0, v162, v161
	v_fmac_f32_e32 v162, v163, v160
	v_fma_f32 v0, -v0, v162, v161
	v_div_fmas_f32 v0, v0, v160, v162
; __device__ __forceinline__ unsigned pkh(float lo, float hi) { f32v2_t v; v.x = lo; v.y = hi; return __builtin_bit_cast(unsigned, __builtin_convertvector(v, bf16v2_t)); }
; __device__ __forceinline__ float bf_lo(unsigned w) { return __uint_as_float(w << 16); }
; __device__ __forceinline__ float bf_hi(unsigned w) { return __uint_as_float(w & 0xffff0000u); }
; __device__ __forceinline__ float sigmoidf_(float x) { return 1.0f / (1.0f + __expf(-x)); }
;     template <int MODE> __device__ __forceinline__ void run(const pg8::f32x4 (&acc)[2][2][4][2], const pg8::Unit& u, int wr, int wc, int fr, int fq) const {
;     ...
;                     if constexpr (MODE == 6) { const u32x4 g = gpre[q];
;                         v[0] *= sigmoidf_(bf_lo(g.x)); v[1] *= sigmoidf_(bf_hi(g.x)); v[2] *= sigmoidf_(bf_lo(g.y)); v[3] *= sigmoidf_(bf_hi(g.y));
;                         v[4] *= sigmoidf_(bf_lo(g.z)); v[5] *= sigmoidf_(bf_hi(g.z)); v[6] *= sigmoidf_(bf_lo(g.w)); v[7] *= sigmoidf_(bf_hi(g.w)); }
;                     u32x4 w; w.x = pkh(v[0], v[1]); w.y = pkh(v[2], v[3]); w.z = pkh(v[4], v[5]); w.w = pkh(v[6], v[7]);
;                     *(u32x4*)(ob + (size_t)row * LDC + col) = w; }
	v_div_fixup_f32 v146, v0, v146, 1.0
	v_lshlrev_b32_e32 v0, 16, v140
	v_pk_mul_f32 v[146:147], v[122:123], v[146:147]
	v_mul_f32_e32 v0, 0xbfb8aa3b, v0
	v_cvt_pk_bf16_f32 v159, v146, v147
	v_exp_f32_e32 v146, v0
	v_and_b32_e32 v0, 0xffff0000, v140
	v_mul_f32_e32 v0, 0xbfb8aa3b, v0
	v_exp_f32_e32 v147, v0
	global_store_dwordx4 v[144:145], v[156:159], off sc0 sc1
	v_pk_add_f32 v[146:147], v[146:147], 1.0 op_sel_hi:[1,0]
	s_nop 0
	v_div_scale_f32 v0, s[28:29], v147, v147, 1.0
	v_rcp_f32_e32 v140, v0
	s_nop 0
	v_fma_f32 v149, -v0, v140, 1.0
	v_fmac_f32_e32 v140, v149, v140
	v_div_scale_f32 v149, vcc, 1.0, v147, 1.0
	v_mul_f32_e32 v156, v149, v140
	v_fma_f32 v157, -v0, v156, v149
	v_fmac_f32_e32 v156, v157, v140
	v_fma_f32 v0, -v0, v156, v149
	v_div_fmas_f32 v0, v0, v140, v156
	v_div_fixup_f32 v147, v0, v147, 1.0
	v_div_scale_f32 v0, s[28:29], v146, v146, 1.0
	v_rcp_f32_e32 v140, v0
	s_nop 0
	v_fma_f32 v149, -v0, v140, 1.0
	v_fmac_f32_e32 v140, v149, v140
	v_div_scale_f32 v149, vcc, 1.0, v146, 1.0
	v_mul_f32_e32 v156, v149, v140
	v_fma_f32 v157, -v0, v156, v149
	v_fmac_f32_e32 v156, v157, v140
	v_fma_f32 v0, -v0, v156, v149
	v_div_fmas_f32 v0, v0, v140, v156
	v_div_fixup_f32 v146, v0, v146, 1.0
	v_lshlrev_b32_e32 v0, 16, v141
	v_mul_f32_e32 v0, 0xbfb8aa3b, v0
	v_exp_f32_e32 v140, v0
	v_and_b32_e32 v0, 0xffff0000, v141
	v_mul_f32_e32 v0, 0xbfb8aa3b, v0
	v_exp_f32_e32 v141, v0
	v_pk_mul_f32 v[146:147], v[124:125], v[146:147]
	v_pk_add_f32 v[140:141], v[140:141], 1.0 op_sel_hi:[1,0]
	s_nop 0
	v_div_scale_f32 v0, s[28:29], v141, v141, 1.0
	v_rcp_f32_e32 v149, v0
	s_nop 0
	v_fma_f32 v156, -v0, v149, 1.0
	v_fmac_f32_e32 v149, v156, v149
	v_div_scale_f32 v156, vcc, 1.0, v141, 1.0
	v_mul_f32_e32 v157, v156, v149
	v_fma_f32 v158, -v0, v157, v156
	v_fmac_f32_e32 v157, v158, v149
	v_fma_f32 v0, -v0, v157, v156
	v_div_fmas_f32 v0, v0, v149, v157
	v_div_fixup_f32 v141, v0, v141, 1.0
	v_div_scale_f32 v0, s[28:29], v140, v140, 1.0
	v_rcp_f32_e32 v149, v0
	s_nop 0
	v_fma_f32 v156, -v0, v149, 1.0
	v_fmac_f32_e32 v149, v156, v149
	v_div_scale_f32 v156, vcc, 1.0, v140, 1.0
	v_mul_f32_e32 v157, v156, v149
	v_fma_f32 v158, -v0, v157, v156
	v_fmac_f32_e32 v157, v158, v149
	v_fma_f32 v0, -v0, v157, v156
	v_div_fmas_f32 v0, v0, v149, v157
	v_div_fixup_f32 v140, v0, v140, 1.0
	v_lshlrev_b32_e32 v0, 16, v142
	v_mul_f32_e32 v0, 0xbfb8aa3b, v0
	v_pk_mul_f32 v[156:157], v[126:127], v[140:141]
	v_exp_f32_e32 v140, v0
	v_and_b32_e32 v0, 0xffff0000, v142
	v_mul_f32_e32 v0, 0xbfb8aa3b, v0
	v_exp_f32_e32 v141, v0
	s_nop 0
	v_pk_add_f32 v[140:141], v[140:141], 1.0 op_sel_hi:[1,0]
	s_nop 0
	v_div_scale_f32 v0, s[28:29], v141, v141, 1.0
	v_rcp_f32_e32 v142, v0
	s_nop 0
	v_fma_f32 v149, -v0, v142, 1.0
	v_fmac_f32_e32 v142, v149, v142
	v_div_scale_f32 v149, vcc, 1.0, v141, 1.0
	v_mul_f32_e32 v158, v149, v142
	v_fma_f32 v159, -v0, v158, v149
	v_fmac_f32_e32 v158, v159, v142
	v_fma_f32 v0, -v0, v158, v149
	v_div_fmas_f32 v0, v0, v142, v158
	v_div_fixup_f32 v141, v0, v141, 1.0
	v_div_scale_f32 v0, s[28:29], v140, v140, 1.0
	v_rcp_f32_e32 v142, v0
	s_nop 0
	v_fma_f32 v149, -v0, v142, 1.0
	v_fmac_f32_e32 v142, v149, v142
	v_div_scale_f32 v149, vcc, 1.0, v140, 1.0
	v_mul_f32_e32 v158, v149, v142
	v_fma_f32 v159, -v0, v158, v149
	v_fmac_f32_e32 v158, v159, v142
	v_fma_f32 v0, -v0, v158, v149
	v_div_fmas_f32 v0, v0, v142, v158
	v_div_fixup_f32 v140, v0, v140, 1.0
	v_lshlrev_b32_e32 v0, 16, v143
	v_mul_f32_e32 v0, 0xbfb8aa3b, v0
	v_pk_mul_f32 v[158:159], v[128:129], v[140:141]
	v_exp_f32_e32 v140, v0
	v_and_b32_e32 v0, 0xffff0000, v143
	v_mul_f32_e32 v0, 0xbfb8aa3b, v0
	v_exp_f32_e32 v141, v0
	s_nop 0
	v_pk_add_f32 v[140:141], v[140:141], 1.0 op_sel_hi:[1,0]
	s_nop 0
	v_div_scale_f32 v0, s[28:29], v141, v141, 1.0
	v_rcp_f32_e32 v142, v0
	s_nop 0
	v_fma_f32 v143, -v0, v142, 1.0
	v_fmac_f32_e32 v142, v143, v142
	v_div_scale_f32 v143, vcc, 1.0, v141, 1.0
	v_mul_f32_e32 v149, v143, v142
	v_fma_f32 v160, -v0, v149, v143
	v_fmac_f32_e32 v149, v160, v142
	v_fma_f32 v0, -v0, v149, v143
	v_div_fmas_f32 v0, v0, v142, v149
	v_div_fixup_f32 v141, v0, v141, 1.0
	v_div_scale_f32 v0, s[28:29], v140, v140, 1.0
	v_rcp_f32_e32 v142, v0
	s_nop 0
	v_fma_f32 v143, -v0, v142, 1.0
	v_fmac_f32_e32 v142, v143, v142
	v_div_scale_f32 v143, vcc, 1.0, v140, 1.0
	v_mul_f32_e32 v149, v143, v142
	v_fma_f32 v160, -v0, v149, v143
	v_fmac_f32_e32 v149, v160, v142
	v_fma_f32 v0, -v0, v149, v143
	v_div_fmas_f32 v0, v0, v142, v149
	v_div_fixup_f32 v140, v0, v140, 1.0
	v_pk_mul_f32 v[160:161], v[130:131], v[140:141]
	v_lshlrev_b32_e32 v0, 16, v136
	v_cvt_pk_bf16_f32 v140, v146, v147
	v_cvt_pk_bf16_f32 v141, v156, v157
	v_cvt_pk_bf16_f32 v142, v158, v159
	v_cvt_pk_bf16_f32 v143, v160, v161
	v_mul_f32_e32 v0, 0xbfb8aa3b, v0
	global_store_dwordx4 v[144:145], v[140:143], off offset:256 sc0 sc1
	s_nop 1
	v_exp_f32_e32 v140, v0
	v_and_b32_e32 v0, 0xffff0000, v136
	v_mul_f32_e32 v0, 0xbfb8aa3b, v0
	v_exp_f32_e32 v141, v0
	s_nop 0
	v_pk_add_f32 v[140:141], v[140:141], 1.0 op_sel_hi:[1,0]
	s_nop 0
	v_div_scale_f32 v0, s[28:29], v141, v141, 1.0
	v_rcp_f32_e32 v136, v0
	s_nop 0
	v_fma_f32 v142, -v0, v136, 1.0
	v_fmac_f32_e32 v136, v142, v136
	v_div_scale_f32 v142, vcc, 1.0, v141, 1.0
	v_mul_f32_e32 v143, v142, v136
	v_fma_f32 v144, -v0, v143, v142
	v_fmac_f32_e32 v143, v144, v136
	v_fma_f32 v0, -v0, v143, v142
	v_div_fmas_f32 v0, v0, v136, v143
	v_div_fixup_f32 v141, v0, v141, 1.0
	v_div_scale_f32 v0, s[28:29], v140, v140, 1.0
	v_rcp_f32_e32 v136, v0
	s_nop 0
	v_fma_f32 v142, -v0, v136, 1.0
	v_fmac_f32_e32 v136, v142, v136
	v_div_scale_f32 v142, vcc, 1.0, v140, 1.0
	v_mul_f32_e32 v143, v142, v136
	v_fma_f32 v144, -v0, v143, v142
; __device__ __forceinline__ unsigned pkh(float lo, float hi) { f32v2_t v; v.x = lo; v.y = hi; return __builtin_bit_cast(unsigned, __builtin_convertvector(v, bf16v2_t)); }
; __device__ __forceinline__ float bf_lo(unsigned w) { return __uint_as_float(w << 16); }
; __device__ __forceinline__ float bf_hi(unsigned w) { return __uint_as_float(w & 0xffff0000u); }
; __device__ __forceinline__ float sigmoidf_(float x) { return 1.0f / (1.0f + __expf(-x)); }
;     template <int MODE> __device__ __forceinline__ void run(const pg8::f32x4 (&acc)[2][2][4][2], const pg8::Unit& u, int wr, int wc, int fr, int fq) const {
;     ...
;                     if constexpr (MODE == 6) { const u32x4 g = gpre[q];
;                         v[0] *= sigmoidf_(bf_lo(g.x)); v[1] *= sigmoidf_(bf_hi(g.x)); v[2] *= sigmoidf_(bf_lo(g.y)); v[3] *= sigmoidf_(bf_hi(g.y));
;                         v[4] *= sigmoidf_(bf_lo(g.z)); v[5] *= sigmoidf_(bf_hi(g.z)); v[6] *= sigmoidf_(bf_lo(g.w)); v[7] *= sigmoidf_(bf_hi(g.w)); }
;                     u32x4 w; w.x = pkh(v[0], v[1]); w.y = pkh(v[2], v[3]); w.z = pkh(v[4], v[5]); w.w = pkh(v[6], v[7]);
;                     *(u32x4*)(ob + (size_t)row * LDC + col) = w; }
	v_fmac_f32_e32 v143, v144, v136
	v_fma_f32 v0, -v0, v143, v142
	v_div_fmas_f32 v0, v0, v136, v143
	v_div_fixup_f32 v140, v0, v140, 1.0
	v_lshlrev_b32_e32 v0, 16, v137
	v_mul_f32_e32 v0, 0xbfb8aa3b, v0
	v_exp_f32_e32 v136, v0
	v_and_b32_e32 v0, 0xffff0000, v137
	v_mul_f32_e32 v0, 0xbfb8aa3b, v0
	v_exp_f32_e32 v137, v0
	v_pk_mul_f32 v[140:141], v[100:101], v[140:141]
	v_pk_add_f32 v[136:137], v[136:137], 1.0 op_sel_hi:[1,0]
	s_nop 0
	v_div_scale_f32 v0, s[28:29], v137, v137, 1.0
	v_rcp_f32_e32 v142, v0
	s_nop 0
	v_fma_f32 v143, -v0, v142, 1.0
	v_fmac_f32_e32 v142, v143, v142
	v_div_scale_f32 v143, vcc, 1.0, v137, 1.0
	v_mul_f32_e32 v144, v143, v142
	v_fma_f32 v145, -v0, v144, v143
	v_fmac_f32_e32 v144, v145, v142
	v_fma_f32 v0, -v0, v144, v143
	v_div_fmas_f32 v0, v0, v142, v144
	v_div_fixup_f32 v137, v0, v137, 1.0
	v_div_scale_f32 v0, s[28:29], v136, v136, 1.0
	v_rcp_f32_e32 v142, v0
	s_nop 0
	v_fma_f32 v143, -v0, v142, 1.0
	v_fmac_f32_e32 v142, v143, v142
	v_div_scale_f32 v143, vcc, 1.0, v136, 1.0
	v_mul_f32_e32 v144, v143, v142
	v_fma_f32 v145, -v0, v144, v143
	v_fmac_f32_e32 v144, v145, v142
	v_fma_f32 v0, -v0, v144, v143
	v_div_fmas_f32 v0, v0, v142, v144
	v_div_fixup_f32 v136, v0, v136, 1.0
	v_lshlrev_b32_e32 v0, 16, v138
	v_mul_f32_e32 v0, 0xbfb8aa3b, v0
	v_exp_f32_e32 v142, v0
	v_and_b32_e32 v0, 0xffff0000, v138
	v_mul_f32_e32 v0, 0xbfb8aa3b, v0
	v_exp_f32_e32 v143, v0
	v_pk_mul_f32 v[136:137], v[102:103], v[136:137]
	v_pk_add_f32 v[142:143], v[142:143], 1.0 op_sel_hi:[1,0]
	s_nop 0
	v_div_scale_f32 v0, s[28:29], v143, v143, 1.0
	v_rcp_f32_e32 v138, v0
	s_nop 0
	v_fma_f32 v144, -v0, v138, 1.0
	v_fmac_f32_e32 v138, v144, v138
	v_div_scale_f32 v144, vcc, 1.0, v143, 1.0
	v_mul_f32_e32 v145, v144, v138
	v_fma_f32 v146, -v0, v145, v144
	v_fmac_f32_e32 v145, v146, v138
	v_fma_f32 v0, -v0, v145, v144
	v_div_fmas_f32 v0, v0, v138, v145
	v_div_fixup_f32 v143, v0, v143, 1.0
	v_div_scale_f32 v0, s[28:29], v142, v142, 1.0
	v_rcp_f32_e32 v138, v0
	s_nop 0
	v_fma_f32 v144, -v0, v138, 1.0
	v_fmac_f32_e32 v138, v144, v138
	v_div_scale_f32 v144, vcc, 1.0, v142, 1.0
	v_mul_f32_e32 v145, v144, v138
	v_fma_f32 v146, -v0, v145, v144
	v_fmac_f32_e32 v145, v146, v138
	v_fma_f32 v0, -v0, v145, v144
	v_div_fmas_f32 v0, v0, v138, v145
	v_div_fixup_f32 v142, v0, v142, 1.0
	v_lshlrev_b32_e32 v0, 16, v139
	v_mul_f32_e32 v0, 0xbfb8aa3b, v0
	v_exp_f32_e32 v138, v0
	v_and_b32_e32 v0, 0xffff0000, v139
	v_mul_f32_e32 v0, 0xbfb8aa3b, v0
	v_exp_f32_e32 v139, v0
	v_pk_mul_f32 v[142:143], v[104:105], v[142:143]
	v_pk_add_f32 v[138:139], v[138:139], 1.0 op_sel_hi:[1,0]
	s_nop 0
	v_div_scale_f32 v0, s[28:29], v139, v139, 1.0
	v_rcp_f32_e32 v144, v0
	s_nop 0
	v_fma_f32 v145, -v0, v144, 1.0
	v_fmac_f32_e32 v144, v145, v144
	v_div_scale_f32 v145, vcc, 1.0, v139, 1.0
	v_mul_f32_e32 v146, v145, v144
	v_fma_f32 v147, -v0, v146, v145
	v_fmac_f32_e32 v146, v147, v144
	v_fma_f32 v0, -v0, v146, v145
	v_div_fmas_f32 v0, v0, v144, v146
	v_div_fixup_f32 v139, v0, v139, 1.0
	v_div_scale_f32 v0, s[28:29], v138, v138, 1.0
	v_rcp_f32_e32 v144, v0
	s_nop 0
	v_fma_f32 v145, -v0, v144, 1.0
	v_fmac_f32_e32 v144, v145, v144
	v_div_scale_f32 v145, vcc, 1.0, v138, 1.0
	v_mul_f32_e32 v146, v145, v144
	v_fma_f32 v147, -v0, v146, v145
	v_fmac_f32_e32 v146, v147, v144
	v_fma_f32 v0, -v0, v146, v145
	v_div_fmas_f32 v0, v0, v144, v146
	v_div_fixup_f32 v138, v0, v138, 1.0
	v_pk_mul_f32 v[144:145], v[106:107], v[138:139]
	v_cvt_pk_bf16_f32 v139, v136, v137
	v_lshlrev_b64 v[136:137], 12, v[154:155]
	v_lshl_add_u64 v[136:137], s[10:11], 0, v[136:137]
	v_lshlrev_b32_e32 v0, 16, v132
	v_cvt_pk_bf16_f32 v138, v140, v141
	v_cvt_pk_bf16_f32 v140, v142, v143
	v_cvt_pk_bf16_f32 v141, v144, v145
	v_lshl_add_u64 v[136:137], v[136:137], 0, v[2:3]
	v_mul_f32_e32 v0, 0xbfb8aa3b, v0
	global_store_dwordx4 v[136:137], v[138:141], off sc0 sc1
	v_add_u32_e32 v154, 32, v148
	v_ashrrev_i32_e32 v155, 31, v154
	v_exp_f32_e32 v138, v0
	v_and_b32_e32 v0, 0xffff0000, v132
	v_mul_f32_e32 v0, 0xbfb8aa3b, v0
	v_exp_f32_e32 v139, v0
	s_nop 0
	v_pk_add_f32 v[138:139], v[138:139], 1.0 op_sel_hi:[1,0]
	s_nop 0
	v_div_scale_f32 v0, s[28:29], v139, v139, 1.0
	v_rcp_f32_e32 v132, v0
	s_nop 0
	v_fma_f32 v140, -v0, v132, 1.0
	v_fmac_f32_e32 v132, v140, v132
	v_div_scale_f32 v140, vcc, 1.0, v139, 1.0
	v_mul_f32_e32 v141, v140, v132
	v_fma_f32 v142, -v0, v141, v140
	v_fmac_f32_e32 v141, v142, v132
	v_fma_f32 v0, -v0, v141, v140
	v_div_fmas_f32 v0, v0, v132, v141
	v_div_fixup_f32 v139, v0, v139, 1.0
	v_div_scale_f32 v0, s[28:29], v138, v138, 1.0
	v_rcp_f32_e32 v132, v0
	s_nop 0
	v_fma_f32 v140, -v0, v132, 1.0
	v_fmac_f32_e32 v132, v140, v132
	v_div_scale_f32 v140, vcc, 1.0, v138, 1.0
	v_mul_f32_e32 v141, v140, v132
	v_fma_f32 v142, -v0, v141, v140
	v_fmac_f32_e32 v141, v142, v132
	v_fma_f32 v0, -v0, v141, v140
	v_div_fmas_f32 v0, v0, v132, v141
	v_div_fixup_f32 v138, v0, v138, 1.0
	v_lshlrev_b32_e32 v0, 16, v133
	v_mul_f32_e32 v0, 0xbfb8aa3b, v0
	v_exp_f32_e32 v132, v0
	v_and_b32_e32 v0, 0xffff0000, v133
	v_mul_f32_e32 v0, 0xbfb8aa3b, v0
	v_exp_f32_e32 v133, v0
	v_pk_mul_f32 v[138:139], v[108:109], v[138:139]
	v_pk_add_f32 v[132:133], v[132:133], 1.0 op_sel_hi:[1,0]
	s_nop 0
	v_div_scale_f32 v0, s[28:29], v133, v133, 1.0
	v_rcp_f32_e32 v140, v0
	s_nop 0
	v_fma_f32 v141, -v0, v140, 1.0
	v_fmac_f32_e32 v140, v141, v140
	v_div_scale_f32 v141, vcc, 1.0, v133, 1.0
	v_mul_f32_e32 v142, v141, v140
	v_fma_f32 v143, -v0, v142, v141
	v_fmac_f32_e32 v142, v143, v140
	v_fma_f32 v0, -v0, v142, v141
	v_div_fmas_f32 v0, v0, v140, v142
	v_div_fixup_f32 v133, v0, v133, 1.0
	v_div_scale_f32 v0, s[28:29], v132, v132, 1.0
	v_rcp_f32_e32 v140, v0
	s_nop 0
; __device__ __forceinline__ unsigned pkh(float lo, float hi) { f32v2_t v; v.x = lo; v.y = hi; return __builtin_bit_cast(unsigned, __builtin_convertvector(v, bf16v2_t)); }
; __device__ __forceinline__ float bf_lo(unsigned w) { return __uint_as_float(w << 16); }
; __device__ __forceinline__ float bf_hi(unsigned w) { return __uint_as_float(w & 0xffff0000u); }
; __device__ __forceinline__ float sigmoidf_(float x) { return 1.0f / (1.0f + __expf(-x)); }
;     template <int MODE> __device__ __forceinline__ void run(const pg8::f32x4 (&acc)[2][2][4][2], const pg8::Unit& u, int wr, int wc, int fr, int fq) const {
;     ...
;                 if constexpr (MODE == 6) {
; #pragma unroll
;                     for (int q = 0; q < 4; ++q) { const int m = 2 * mp + (q >> 1), bj = q & 1; const int row = u.pm * 256 + ai * 128 + wr * 64 + m * 16 + fr, col = u.pn * 256 + bj * 128 + wc * 32 + 8 * fq;
;                         gpre[q] = *(const u32x4*)(proj + (size_t)row * NP + OFF_MG + 2 * DM + col); }
;                 }
; #pragma unroll
;                 for (int q = 0; q < 4; ++q) { const int m = 2 * mp + (q >> 1), bj = q & 1; const int row = u.pm * 256 + ai * 128 + wr * 64 + m * 16 + fr, col = u.pn * 256 + bj * 128 + wc * 32 + 8 * fq;
;                     const pg8::f32x4 t0 = acc[ai][bj][m][0], t1 = acc[ai][bj][m][1];
;                     float v[8] = {t0[0], t0[1], t0[2], t0[3], t1[0], t1[1], t1[2], t1[3]};
;                     if constexpr (MODE == 5) {
; #pragma unroll
;                         for (int e = 0; e < 8; ++e) { const float r = fmaxf(v[e], 0.f); v[e] = r * r; }
;                     }
;                     if constexpr (MODE == 6) { const u32x4 g = gpre[q];
;                         v[0] *= sigmoidf_(bf_lo(g.x)); v[1] *= sigmoidf_(bf_hi(g.x)); v[2] *= sigmoidf_(bf_lo(g.y)); v[3] *= sigmoidf_(bf_hi(g.y));
;                         v[4] *= sigmoidf_(bf_lo(g.z)); v[5] *= sigmoidf_(bf_hi(g.z)); v[6] *= sigmoidf_(bf_lo(g.w)); v[7] *= sigmoidf_(bf_hi(g.w)); }
;                     u32x4 w; w.x = pkh(v[0], v[1]); w.y = pkh(v[2], v[3]); w.z = pkh(v[4], v[5]); w.w = pkh(v[6], v[7]);
;                     *(u32x4*)(ob + (size_t)row * LDC + col) = w; }
	v_fma_f32 v141, -v0, v140, 1.0
	v_fmac_f32_e32 v140, v141, v140
	v_div_scale_f32 v141, vcc, 1.0, v132, 1.0
	v_mul_f32_e32 v142, v141, v140
	v_fma_f32 v143, -v0, v142, v141
	v_fmac_f32_e32 v142, v143, v140
	v_fma_f32 v0, -v0, v142, v141
	v_div_fmas_f32 v0, v0, v140, v142
	v_div_fixup_f32 v132, v0, v132, 1.0
	v_lshlrev_b32_e32 v0, 16, v134
	v_mul_f32_e32 v0, 0xbfb8aa3b, v0
	v_pk_mul_f32 v[140:141], v[110:111], v[132:133]
	v_exp_f32_e32 v132, v0
	v_and_b32_e32 v0, 0xffff0000, v134
	v_mul_f32_e32 v0, 0xbfb8aa3b, v0
	v_exp_f32_e32 v133, v0
	s_nop 0
	v_pk_add_f32 v[132:133], v[132:133], 1.0 op_sel_hi:[1,0]
	s_nop 0
	v_div_scale_f32 v0, s[28:29], v133, v133, 1.0
	v_rcp_f32_e32 v134, v0
	s_nop 0
	v_fma_f32 v142, -v0, v134, 1.0
	v_fmac_f32_e32 v134, v142, v134
	v_div_scale_f32 v142, vcc, 1.0, v133, 1.0
	v_mul_f32_e32 v143, v142, v134
	v_fma_f32 v144, -v0, v143, v142
	v_fmac_f32_e32 v143, v144, v134
	v_fma_f32 v0, -v0, v143, v142
	v_div_fmas_f32 v0, v0, v134, v143
	v_div_fixup_f32 v133, v0, v133, 1.0
	v_div_scale_f32 v0, s[28:29], v132, v132, 1.0
	v_rcp_f32_e32 v134, v0
	s_nop 0
	v_fma_f32 v142, -v0, v134, 1.0
	v_fmac_f32_e32 v134, v142, v134
	v_div_scale_f32 v142, vcc, 1.0, v132, 1.0
	v_mul_f32_e32 v143, v142, v134
	v_fma_f32 v144, -v0, v143, v142
	v_fmac_f32_e32 v143, v144, v134
	v_fma_f32 v0, -v0, v143, v142
	v_div_fmas_f32 v0, v0, v134, v143
	v_div_fixup_f32 v132, v0, v132, 1.0
	v_lshlrev_b32_e32 v0, 16, v135
	v_mul_f32_e32 v0, 0xbfb8aa3b, v0
	v_pk_mul_f32 v[142:143], v[112:113], v[132:133]
	v_exp_f32_e32 v132, v0
	v_and_b32_e32 v0, 0xffff0000, v135
	v_mul_f32_e32 v0, 0xbfb8aa3b, v0
	v_exp_f32_e32 v133, v0
	s_nop 0
	v_pk_add_f32 v[132:133], v[132:133], 1.0 op_sel_hi:[1,0]
	s_nop 0
	v_div_scale_f32 v0, s[28:29], v133, v133, 1.0
	v_rcp_f32_e32 v134, v0
	s_nop 0
	v_fma_f32 v135, -v0, v134, 1.0
	v_fmac_f32_e32 v134, v135, v134
	v_div_scale_f32 v135, vcc, 1.0, v133, 1.0
	v_mul_f32_e32 v144, v135, v134
	v_fma_f32 v145, -v0, v144, v135
	v_fmac_f32_e32 v144, v145, v134
	v_fma_f32 v0, -v0, v144, v135
	v_div_fmas_f32 v0, v0, v134, v144
	v_div_fixup_f32 v133, v0, v133, 1.0
	v_div_scale_f32 v0, s[28:29], v132, v132, 1.0
	v_rcp_f32_e32 v134, v0
	s_nop 0
	v_fma_f32 v135, -v0, v134, 1.0
	v_fmac_f32_e32 v134, v135, v134
	v_div_scale_f32 v135, vcc, 1.0, v132, 1.0
	v_mul_f32_e32 v144, v135, v134
	v_fma_f32 v145, -v0, v144, v135
	v_fmac_f32_e32 v144, v145, v134
	v_fma_f32 v0, -v0, v144, v135
	v_div_fmas_f32 v0, v0, v134, v144
	v_div_fixup_f32 v132, v0, v132, 1.0
	v_pk_mul_f32 v[144:145], v[114:115], v[132:133]
	v_cvt_pk_bf16_f32 v132, v138, v139
	v_cvt_pk_bf16_f32 v133, v140, v141
	v_cvt_pk_bf16_f32 v134, v142, v143
	v_cvt_pk_bf16_f32 v135, v144, v145
	global_store_dwordx4 v[136:137], v[132:135], off offset:256 sc0 sc1
	v_add_u32_e32 v0, 48, v148
	s_nop 0
	v_mad_i64_i32 v[132:133], s[28:29], v154, s76, v[150:151]
	v_lshl_add_u64 v[132:133], v[132:133], 0, s[30:31]
	v_lshl_add_u64 v[134:135], v[132:133], 0, v[2:3]
	global_load_dwordx4 v[144:147], v[134:135], off
	v_lshl_add_u64 v[132:133], v[132:133], 0, v[152:153]
	global_load_dwordx4 v[140:143], v[132:133], off
	v_mad_i64_i32 v[132:133], s[28:29], v0, s76, v[150:151]
	v_lshl_add_u64 v[132:133], v[132:133], 0, s[30:31]
	v_lshl_add_u64 v[134:135], v[132:133], 0, v[2:3]
	v_lshl_add_u64 v[132:133], v[132:133], 0, v[152:153]
	global_load_dwordx4 v[136:139], v[134:135], off
	s_waitcnt vmcnt(0)
	v_lshlrev_b32_e32 v0, 16, v144
	v_mul_f32_e32 v0, 0xbfb8aa3b, v0
	v_exp_f32_e32 v156, v0
	v_and_b32_e32 v0, 0xffff0000, v144
	v_mul_f32_e32 v0, 0xbfb8aa3b, v0
	v_exp_f32_e32 v157, v0
	global_load_dwordx4 v[132:135], v[132:133], off
	v_pk_add_f32 v[156:157], v[156:157], 1.0 op_sel_hi:[1,0]
	s_nop 0
	v_div_scale_f32 v0, s[28:29], v157, v157, 1.0
	v_rcp_f32_e32 v144, v0
	s_nop 0
	v_fma_f32 v149, -v0, v144, 1.0
	v_fmac_f32_e32 v144, v149, v144
	v_div_scale_f32 v149, vcc, 1.0, v157, 1.0
	v_mul_f32_e32 v158, v149, v144
	v_fma_f32 v159, -v0, v158, v149
	v_fmac_f32_e32 v158, v159, v144
	v_fma_f32 v0, -v0, v158, v149
	v_div_fmas_f32 v0, v0, v144, v158
	v_div_fixup_f32 v157, v0, v157, 1.0
	v_div_scale_f32 v0, s[28:29], v156, v156, 1.0
	v_rcp_f32_e32 v144, v0
	s_nop 0
	v_fma_f32 v149, -v0, v144, 1.0
	v_fmac_f32_e32 v144, v149, v144
	v_div_scale_f32 v149, vcc, 1.0, v156, 1.0
	v_mul_f32_e32 v158, v149, v144
	v_fma_f32 v159, -v0, v158, v149
	v_fmac_f32_e32 v158, v159, v144
	v_fma_f32 v0, -v0, v158, v149
	v_div_fmas_f32 v0, v0, v144, v158
	v_div_fixup_f32 v156, v0, v156, 1.0
	v_lshlrev_b32_e32 v0, 16, v145
	v_mul_f32_e32 v0, 0xbfb8aa3b, v0
	v_exp_f32_e32 v144, v0
	v_and_b32_e32 v0, 0xffff0000, v145
	v_mul_f32_e32 v0, 0xbfb8aa3b, v0
	v_exp_f32_e32 v145, v0
	v_pk_mul_f32 v[156:157], v[76:77], v[156:157]
	v_pk_add_f32 v[144:145], v[144:145], 1.0 op_sel_hi:[1,0]
	s_nop 0
	v_div_scale_f32 v0, s[28:29], v145, v145, 1.0
	v_rcp_f32_e32 v149, v0
	v_cvt_pk_bf16_f32 v156, v156, v157
	v_fma_f32 v158, -v0, v149, 1.0
	v_fmac_f32_e32 v149, v158, v149
	v_div_scale_f32 v158, vcc, 1.0, v145, 1.0
	v_mul_f32_e32 v159, v158, v149
	v_fma_f32 v160, -v0, v159, v158
	v_fmac_f32_e32 v159, v160, v149
	v_fma_f32 v0, -v0, v159, v158
	v_div_fmas_f32 v0, v0, v149, v159
	v_div_fixup_f32 v145, v0, v145, 1.0
	v_div_scale_f32 v0, s[28:29], v144, v144, 1.0
	v_rcp_f32_e32 v149, v0
	s_nop 0
	v_fma_f32 v158, -v0, v149, 1.0
	v_fmac_f32_e32 v149, v158, v149
	v_div_scale_f32 v158, vcc, 1.0, v144, 1.0
	v_mul_f32_e32 v159, v158, v149
	v_fma_f32 v160, -v0, v159, v158
	v_fmac_f32_e32 v159, v160, v149
	v_fma_f32 v0, -v0, v159, v158
	v_div_fmas_f32 v0, v0, v149, v159
	v_div_fixup_f32 v144, v0, v144, 1.0
	v_lshlrev_b32_e32 v0, 16, v146
	v_mul_f32_e32 v0, 0xbfb8aa3b, v0
	v_exp_f32_e32 v158, v0
; __device__ __forceinline__ unsigned pkh(float lo, float hi) { f32v2_t v; v.x = lo; v.y = hi; return __builtin_bit_cast(unsigned, __builtin_convertvector(v, bf16v2_t)); }
; __device__ __forceinline__ float bf_lo(unsigned w) { return __uint_as_float(w << 16); }
; __device__ __forceinline__ float bf_hi(unsigned w) { return __uint_as_float(w & 0xffff0000u); }
; __device__ __forceinline__ float sigmoidf_(float x) { return 1.0f / (1.0f + __expf(-x)); }
;     template <int MODE> __device__ __forceinline__ void run(const pg8::f32x4 (&acc)[2][2][4][2], const pg8::Unit& u, int wr, int wc, int fr, int fq) const {
;     ...
;                     if constexpr (MODE == 6) { const u32x4 g = gpre[q];
;                         v[0] *= sigmoidf_(bf_lo(g.x)); v[1] *= sigmoidf_(bf_hi(g.x)); v[2] *= sigmoidf_(bf_lo(g.y)); v[3] *= sigmoidf_(bf_hi(g.y));
;                         v[4] *= sigmoidf_(bf_lo(g.z)); v[5] *= sigmoidf_(bf_hi(g.z)); v[6] *= sigmoidf_(bf_lo(g.w)); v[7] *= sigmoidf_(bf_hi(g.w)); }
;                     u32x4 w; w.x = pkh(v[0], v[1]); w.y = pkh(v[2], v[3]); w.z = pkh(v[4], v[5]); w.w = pkh(v[6], v[7]);
;                     *(u32x4*)(ob + (size_t)row * LDC + col) = w; }
	v_and_b32_e32 v0, 0xffff0000, v146
	v_mul_f32_e32 v0, 0xbfb8aa3b, v0
	v_exp_f32_e32 v159, v0
	v_pk_mul_f32 v[144:145], v[78:79], v[144:145]
	v_pk_add_f32 v[158:159], v[158:159], 1.0 op_sel_hi:[1,0]
	s_nop 0
	v_div_scale_f32 v0, s[28:29], v159, v159, 1.0
	v_rcp_f32_e32 v146, v0
	v_cvt_pk_bf16_f32 v157, v144, v145
	v_lshlrev_b64 v[144:145], 12, v[154:155]
	v_lshl_add_u64 v[144:145], s[10:11], 0, v[144:145]
	v_fma_f32 v149, -v0, v146, 1.0
	v_fmac_f32_e32 v146, v149, v146
	v_div_scale_f32 v149, vcc, 1.0, v159, 1.0
	v_mul_f32_e32 v160, v149, v146
	v_fma_f32 v161, -v0, v160, v149
	v_fmac_f32_e32 v160, v161, v146
	v_fma_f32 v0, -v0, v160, v149
	v_div_fmas_f32 v0, v0, v146, v160
	v_div_fixup_f32 v159, v0, v159, 1.0
	v_div_scale_f32 v0, s[28:29], v158, v158, 1.0
	v_rcp_f32_e32 v146, v0
	v_lshl_add_u64 v[144:145], v[144:145], 0, v[2:3]
	v_fma_f32 v149, -v0, v146, 1.0
	v_fmac_f32_e32 v146, v149, v146
	v_div_scale_f32 v149, vcc, 1.0, v158, 1.0
	v_mul_f32_e32 v160, v149, v146
	v_fma_f32 v161, -v0, v160, v149
	v_fmac_f32_e32 v160, v161, v146
	v_fma_f32 v0, -v0, v160, v149
	v_div_fmas_f32 v0, v0, v146, v160
	v_div_fixup_f32 v158, v0, v158, 1.0
	v_lshlrev_b32_e32 v0, 16, v147
	v_mul_f32_e32 v0, 0xbfb8aa3b, v0
	v_exp_f32_e32 v146, v0
	v_and_b32_e32 v0, 0xffff0000, v147
	v_mul_f32_e32 v0, 0xbfb8aa3b, v0
	v_exp_f32_e32 v147, v0
	v_pk_mul_f32 v[158:159], v[80:81], v[158:159]
	v_pk_add_f32 v[146:147], v[146:147], 1.0 op_sel_hi:[1,0]
	s_nop 0
	v_div_scale_f32 v0, s[28:29], v147, v147, 1.0
	v_rcp_f32_e32 v149, v0
	v_cvt_pk_bf16_f32 v158, v158, v159
	v_fma_f32 v160, -v0, v149, 1.0
	v_fmac_f32_e32 v149, v160, v149
	v_div_scale_f32 v160, vcc, 1.0, v147, 1.0
	v_mul_f32_e32 v161, v160, v149
	v_fma_f32 v162, -v0, v161, v160
	v_fmac_f32_e32 v161, v162, v149
	v_fma_f32 v0, -v0, v161, v160
	v_div_fmas_f32 v0, v0, v149, v161
	v_div_fixup_f32 v147, v0, v147, 1.0
	v_div_scale_f32 v0, s[28:29], v146, v146, 1.0
	v_rcp_f32_e32 v149, v0
	s_nop 0
	v_fma_f32 v160, -v0, v149, 1.0
	v_fmac_f32_e32 v149, v160, v149
	v_div_scale_f32 v160, vcc, 1.0, v146, 1.0
	v_mul_f32_e32 v161, v160, v149
	v_fma_f32 v162, -v0, v161, v160
	v_fmac_f32_e32 v161, v162, v149
	v_fma_f32 v0, -v0, v161, v160
	v_div_fmas_f32 v0, v0, v149, v161
	v_div_fixup_f32 v146, v0, v146, 1.0
	v_lshlrev_b32_e32 v0, 16, v140
	v_pk_mul_f32 v[146:147], v[82:83], v[146:147]
	v_mul_f32_e32 v0, 0xbfb8aa3b, v0
	v_cvt_pk_bf16_f32 v159, v146, v147
	v_exp_f32_e32 v146, v0
	v_and_b32_e32 v0, 0xffff0000, v140
	v_mul_f32_e32 v0, 0xbfb8aa3b, v0
	v_exp_f32_e32 v147, v0
	global_store_dwordx4 v[144:145], v[156:159], off sc0 sc1
	v_pk_add_f32 v[146:147], v[146:147], 1.0 op_sel_hi:[1,0]
	s_nop 0
	v_div_scale_f32 v0, s[28:29], v147, v147, 1.0
	v_rcp_f32_e32 v140, v0
	s_nop 0
	v_fma_f32 v149, -v0, v140, 1.0
	v_fmac_f32_e32 v140, v149, v140
	v_div_scale_f32 v149, vcc, 1.0, v147, 1.0
	v_mul_f32_e32 v154, v149, v140
	v_fma_f32 v155, -v0, v154, v149
	v_fmac_f32_e32 v154, v155, v140
	v_fma_f32 v0, -v0, v154, v149
	v_div_fmas_f32 v0, v0, v140, v154
	v_div_fixup_f32 v147, v0, v147, 1.0
	v_div_scale_f32 v0, s[28:29], v146, v146, 1.0
	v_rcp_f32_e32 v140, v0
	s_nop 0
	v_fma_f32 v149, -v0, v140, 1.0
	v_fmac_f32_e32 v140, v149, v140
	v_div_scale_f32 v149, vcc, 1.0, v146, 1.0
	v_mul_f32_e32 v154, v149, v140
	v_fma_f32 v155, -v0, v154, v149
	v_fmac_f32_e32 v154, v155, v140
	v_fma_f32 v0, -v0, v154, v149
	v_div_fmas_f32 v0, v0, v140, v154
	v_div_fixup_f32 v146, v0, v146, 1.0
	v_lshlrev_b32_e32 v0, 16, v141
	v_mul_f32_e32 v0, 0xbfb8aa3b, v0
	v_exp_f32_e32 v140, v0
	v_and_b32_e32 v0, 0xffff0000, v141
	v_mul_f32_e32 v0, 0xbfb8aa3b, v0
	v_exp_f32_e32 v141, v0
	v_pk_mul_f32 v[146:147], v[92:93], v[146:147]
	v_pk_add_f32 v[140:141], v[140:141], 1.0 op_sel_hi:[1,0]
	s_nop 0
	v_div_scale_f32 v0, s[28:29], v141, v141, 1.0
	v_rcp_f32_e32 v149, v0
	s_nop 0
	v_fma_f32 v154, -v0, v149, 1.0
	v_fmac_f32_e32 v149, v154, v149
	v_div_scale_f32 v154, vcc, 1.0, v141, 1.0
	v_mul_f32_e32 v155, v154, v149
	v_fma_f32 v156, -v0, v155, v154
	v_fmac_f32_e32 v155, v156, v149
	v_fma_f32 v0, -v0, v155, v154
	v_div_fmas_f32 v0, v0, v149, v155
	v_div_fixup_f32 v141, v0, v141, 1.0
	v_div_scale_f32 v0, s[28:29], v140, v140, 1.0
	v_rcp_f32_e32 v149, v0
	s_nop 0
	v_fma_f32 v154, -v0, v149, 1.0
	v_fmac_f32_e32 v149, v154, v149
	v_div_scale_f32 v154, vcc, 1.0, v140, 1.0
	v_mul_f32_e32 v155, v154, v149
	v_fma_f32 v156, -v0, v155, v154
	v_fmac_f32_e32 v155, v156, v149
	v_fma_f32 v0, -v0, v155, v154
	v_div_fmas_f32 v0, v0, v149, v155
	v_div_fixup_f32 v140, v0, v140, 1.0
	v_lshlrev_b32_e32 v0, 16, v142
	v_mul_f32_e32 v0, 0xbfb8aa3b, v0
	v_pk_mul_f32 v[154:155], v[94:95], v[140:141]
	v_exp_f32_e32 v140, v0
	v_and_b32_e32 v0, 0xffff0000, v142
	v_mul_f32_e32 v0, 0xbfb8aa3b, v0
	v_exp_f32_e32 v141, v0
	s_nop 0
	v_pk_add_f32 v[140:141], v[140:141], 1.0 op_sel_hi:[1,0]
	s_nop 0
	v_div_scale_f32 v0, s[28:29], v141, v141, 1.0
	v_rcp_f32_e32 v142, v0
	s_nop 0
	v_fma_f32 v149, -v0, v142, 1.0
	v_fmac_f32_e32 v142, v149, v142
	v_div_scale_f32 v149, vcc, 1.0, v141, 1.0
	v_mul_f32_e32 v156, v149, v142
	v_fma_f32 v157, -v0, v156, v149
	v_fmac_f32_e32 v156, v157, v142
	v_fma_f32 v0, -v0, v156, v149
	v_div_fmas_f32 v0, v0, v142, v156
	v_div_fixup_f32 v141, v0, v141, 1.0
	v_div_scale_f32 v0, s[28:29], v140, v140, 1.0
	v_rcp_f32_e32 v142, v0
	s_nop 0
	v_fma_f32 v149, -v0, v142, 1.0
	v_fmac_f32_e32 v142, v149, v142
	v_div_scale_f32 v149, vcc, 1.0, v140, 1.0
	v_mul_f32_e32 v156, v149, v142
	v_fma_f32 v157, -v0, v156, v149
	v_fmac_f32_e32 v156, v157, v142
	v_fma_f32 v0, -v0, v156, v149
	v_div_fmas_f32 v0, v0, v142, v156
	v_div_fixup_f32 v140, v0, v140, 1.0
	v_lshlrev_b32_e32 v0, 16, v143
	v_mul_f32_e32 v0, 0xbfb8aa3b, v0
; __device__ __forceinline__ unsigned pkh(float lo, float hi) { f32v2_t v; v.x = lo; v.y = hi; return __builtin_bit_cast(unsigned, __builtin_convertvector(v, bf16v2_t)); }
; __device__ __forceinline__ float bf_lo(unsigned w) { return __uint_as_float(w << 16); }
; __device__ __forceinline__ float bf_hi(unsigned w) { return __uint_as_float(w & 0xffff0000u); }
; __device__ __forceinline__ float sigmoidf_(float x) { return 1.0f / (1.0f + __expf(-x)); }
;     template <int MODE> __device__ __forceinline__ void run(const pg8::f32x4 (&acc)[2][2][4][2], const pg8::Unit& u, int wr, int wc, int fr, int fq) const {
;     ...
;                     if constexpr (MODE == 6) { const u32x4 g = gpre[q];
;                         v[0] *= sigmoidf_(bf_lo(g.x)); v[1] *= sigmoidf_(bf_hi(g.x)); v[2] *= sigmoidf_(bf_lo(g.y)); v[3] *= sigmoidf_(bf_hi(g.y));
;                         v[4] *= sigmoidf_(bf_lo(g.z)); v[5] *= sigmoidf_(bf_hi(g.z)); v[6] *= sigmoidf_(bf_lo(g.w)); v[7] *= sigmoidf_(bf_hi(g.w)); }
;                     u32x4 w; w.x = pkh(v[0], v[1]); w.y = pkh(v[2], v[3]); w.z = pkh(v[4], v[5]); w.w = pkh(v[6], v[7]);
;                     *(u32x4*)(ob + (size_t)row * LDC + col) = w; }
	v_pk_mul_f32 v[156:157], v[96:97], v[140:141]
	v_exp_f32_e32 v140, v0
	v_and_b32_e32 v0, 0xffff0000, v143
	v_mul_f32_e32 v0, 0xbfb8aa3b, v0
	v_exp_f32_e32 v141, v0
	s_nop 0
	v_pk_add_f32 v[140:141], v[140:141], 1.0 op_sel_hi:[1,0]
	s_nop 0
	v_div_scale_f32 v0, s[28:29], v141, v141, 1.0
	v_rcp_f32_e32 v142, v0
	s_nop 0
	v_fma_f32 v143, -v0, v142, 1.0
	v_fmac_f32_e32 v142, v143, v142
	v_div_scale_f32 v143, vcc, 1.0, v141, 1.0
	v_mul_f32_e32 v149, v143, v142
	v_fma_f32 v158, -v0, v149, v143
	v_fmac_f32_e32 v149, v158, v142
	v_fma_f32 v0, -v0, v149, v143
	v_div_fmas_f32 v0, v0, v142, v149
	v_div_fixup_f32 v141, v0, v141, 1.0
	v_div_scale_f32 v0, s[28:29], v140, v140, 1.0
	v_rcp_f32_e32 v142, v0
	s_nop 0
	v_fma_f32 v143, -v0, v142, 1.0
	v_fmac_f32_e32 v142, v143, v142
	v_div_scale_f32 v143, vcc, 1.0, v140, 1.0
	v_mul_f32_e32 v149, v143, v142
	v_fma_f32 v158, -v0, v149, v143
	v_fmac_f32_e32 v149, v158, v142
	v_fma_f32 v0, -v0, v149, v143
	v_div_fmas_f32 v0, v0, v142, v149
	v_div_fixup_f32 v140, v0, v140, 1.0
	v_pk_mul_f32 v[158:159], v[98:99], v[140:141]
	v_lshlrev_b32_e32 v0, 16, v136
	v_cvt_pk_bf16_f32 v140, v146, v147
	v_cvt_pk_bf16_f32 v141, v154, v155
	v_cvt_pk_bf16_f32 v142, v156, v157
	v_cvt_pk_bf16_f32 v143, v158, v159
	v_mul_f32_e32 v0, 0xbfb8aa3b, v0
	global_store_dwordx4 v[144:145], v[140:143], off offset:256 sc0 sc1
	v_add_u32_e32 v156, 0x80, v148
	v_ashrrev_i32_e32 v157, 31, v156
	v_exp_f32_e32 v142, v0
	v_and_b32_e32 v0, 0xffff0000, v136
	v_mul_f32_e32 v0, 0xbfb8aa3b, v0
	v_exp_f32_e32 v143, v0
	v_or_b32_e32 v140, 48, v148
	v_add_u32_e32 v154, 0x90, v148
	v_pk_add_f32 v[142:143], v[142:143], 1.0 op_sel_hi:[1,0]
	s_nop 0
	v_div_scale_f32 v0, s[28:29], v143, v143, 1.0
	v_rcp_f32_e32 v136, v0
	s_nop 0
	v_fma_f32 v141, -v0, v136, 1.0
	v_fmac_f32_e32 v136, v141, v136
	v_div_scale_f32 v141, vcc, 1.0, v143, 1.0
	v_mul_f32_e32 v144, v141, v136
	v_fma_f32 v145, -v0, v144, v141
	v_fmac_f32_e32 v144, v145, v136
	v_fma_f32 v0, -v0, v144, v141
	v_div_fmas_f32 v0, v0, v136, v144
	v_div_fixup_f32 v143, v0, v143, 1.0
	v_div_scale_f32 v0, s[28:29], v142, v142, 1.0
	v_rcp_f32_e32 v136, v0
	s_nop 0
	v_fma_f32 v141, -v0, v136, 1.0
	v_fmac_f32_e32 v136, v141, v136
	v_div_scale_f32 v141, vcc, 1.0, v142, 1.0
	v_mul_f32_e32 v144, v141, v136
	v_fma_f32 v145, -v0, v144, v141
	v_fmac_f32_e32 v144, v145, v136
	v_fma_f32 v0, -v0, v144, v141
	v_div_fmas_f32 v0, v0, v136, v144
	v_div_fixup_f32 v142, v0, v142, 1.0
	v_lshlrev_b32_e32 v0, 16, v137
	v_mul_f32_e32 v0, 0xbfb8aa3b, v0
	v_exp_f32_e32 v136, v0
	v_and_b32_e32 v0, 0xffff0000, v137
	v_mul_f32_e32 v0, 0xbfb8aa3b, v0
	v_exp_f32_e32 v137, v0
	v_pk_mul_f32 v[142:143], v[44:45], v[142:143]
	v_pk_add_f32 v[136:137], v[136:137], 1.0 op_sel_hi:[1,0]
	s_nop 0
	v_div_scale_f32 v0, s[28:29], v137, v137, 1.0
	v_rcp_f32_e32 v141, v0
	v_cvt_pk_bf16_f32 v142, v142, v143
	v_fma_f32 v144, -v0, v141, 1.0
	v_fmac_f32_e32 v141, v144, v141
	v_div_scale_f32 v144, vcc, 1.0, v137, 1.0
	v_mul_f32_e32 v145, v144, v141
	v_fma_f32 v146, -v0, v145, v144
	v_fmac_f32_e32 v145, v146, v141
	v_fma_f32 v0, -v0, v145, v144
	v_div_fmas_f32 v0, v0, v141, v145
	v_div_fixup_f32 v137, v0, v137, 1.0
	v_div_scale_f32 v0, s[28:29], v136, v136, 1.0
	v_rcp_f32_e32 v141, v0
	s_nop 0
	v_fma_f32 v144, -v0, v141, 1.0
	v_fmac_f32_e32 v141, v144, v141
	v_div_scale_f32 v144, vcc, 1.0, v136, 1.0
	v_mul_f32_e32 v145, v144, v141
	v_fma_f32 v146, -v0, v145, v144
	v_fmac_f32_e32 v145, v146, v141
	v_fma_f32 v0, -v0, v145, v144
	v_div_fmas_f32 v0, v0, v141, v145
	v_div_fixup_f32 v136, v0, v136, 1.0
	v_lshlrev_b32_e32 v0, 16, v138
	v_mul_f32_e32 v0, 0xbfb8aa3b, v0
	v_exp_f32_e32 v144, v0
	v_and_b32_e32 v0, 0xffff0000, v138
	v_mul_f32_e32 v0, 0xbfb8aa3b, v0
	v_exp_f32_e32 v145, v0
	v_pk_mul_f32 v[136:137], v[46:47], v[136:137]
	v_pk_add_f32 v[144:145], v[144:145], 1.0 op_sel_hi:[1,0]
	s_nop 0
	v_div_scale_f32 v0, s[28:29], v145, v145, 1.0
	v_rcp_f32_e32 v138, v0
	v_cvt_pk_bf16_f32 v143, v136, v137
	v_fma_f32 v141, -v0, v138, 1.0
	v_fmac_f32_e32 v138, v141, v138
	v_div_scale_f32 v141, vcc, 1.0, v145, 1.0
	v_mul_f32_e32 v146, v141, v138
	v_fma_f32 v147, -v0, v146, v141
	v_fmac_f32_e32 v146, v147, v138
	v_fma_f32 v0, -v0, v146, v141
	v_div_fmas_f32 v0, v0, v138, v146
	v_div_fixup_f32 v145, v0, v145, 1.0
	v_div_scale_f32 v0, s[28:29], v144, v144, 1.0
	v_rcp_f32_e32 v138, v0
	s_nop 0
	v_fma_f32 v141, -v0, v138, 1.0
	v_fmac_f32_e32 v138, v141, v138
	v_div_scale_f32 v141, vcc, 1.0, v144, 1.0
	v_mul_f32_e32 v146, v141, v138
	v_fma_f32 v147, -v0, v146, v141
	v_fmac_f32_e32 v146, v147, v138
	v_fma_f32 v0, -v0, v146, v141
	v_div_fmas_f32 v0, v0, v138, v146
	v_div_fixup_f32 v144, v0, v144, 1.0
	v_lshlrev_b32_e32 v0, 16, v139
	v_mul_f32_e32 v0, 0xbfb8aa3b, v0
	v_exp_f32_e32 v138, v0
	v_and_b32_e32 v0, 0xffff0000, v139
	v_mul_f32_e32 v0, 0xbfb8aa3b, v0
	v_exp_f32_e32 v139, v0
	v_pk_mul_f32 v[144:145], v[48:49], v[144:145]
	v_pk_add_f32 v[138:139], v[138:139], 1.0 op_sel_hi:[1,0]
	s_nop 0
	v_div_scale_f32 v0, s[28:29], v139, v139, 1.0
	v_rcp_f32_e32 v141, v0
	v_cvt_pk_bf16_f32 v144, v144, v145
	v_fma_f32 v146, -v0, v141, 1.0
	v_fmac_f32_e32 v141, v146, v141
	v_div_scale_f32 v146, vcc, 1.0, v139, 1.0
	v_mul_f32_e32 v147, v146, v141
	v_fma_f32 v149, -v0, v147, v146
	v_fmac_f32_e32 v147, v149, v141
	v_fma_f32 v0, -v0, v147, v146
	v_div_fmas_f32 v0, v0, v141, v147
	v_div_fixup_f32 v139, v0, v139, 1.0
	v_div_scale_f32 v0, s[28:29], v138, v138, 1.0
	v_rcp_f32_e32 v141, v0
	s_nop 0
	v_fma_f32 v146, -v0, v141, 1.0
	v_fmac_f32_e32 v141, v146, v141
	v_div_scale_f32 v146, vcc, 1.0, v138, 1.0
	v_mul_f32_e32 v147, v146, v141
	v_fma_f32 v149, -v0, v147, v146
	v_fmac_f32_e32 v147, v149, v141
	v_fma_f32 v0, -v0, v147, v146
	v_div_fmas_f32 v0, v0, v141, v147
	v_div_fixup_f32 v138, v0, v138, 1.0
	s_waitcnt vmcnt(0)
; __device__ __forceinline__ unsigned pkh(float lo, float hi) { f32v2_t v; v.x = lo; v.y = hi; return __builtin_bit_cast(unsigned, __builtin_convertvector(v, bf16v2_t)); }
; __device__ __forceinline__ float bf_lo(unsigned w) { return __uint_as_float(w << 16); }
; __device__ __forceinline__ float bf_hi(unsigned w) { return __uint_as_float(w & 0xffff0000u); }
; __device__ __forceinline__ float sigmoidf_(float x) { return 1.0f / (1.0f + __expf(-x)); }
;     template <int MODE> __device__ __forceinline__ void run(const pg8::f32x4 (&acc)[2][2][4][2], const pg8::Unit& u, int wr, int wc, int fr, int fq) const {
;     ...
;                 if constexpr (MODE == 6) {
; #pragma unroll
;                     for (int q = 0; q < 4; ++q) { const int m = 2 * mp + (q >> 1), bj = q & 1; const int row = u.pm * 256 + ai * 128 + wr * 64 + m * 16 + fr, col = u.pn * 256 + bj * 128 + wc * 32 + 8 * fq;
;                         gpre[q] = *(const u32x4*)(proj + (size_t)row * NP + OFF_MG + 2 * DM + col); }
;                 }
; #pragma unroll
;                 for (int q = 0; q < 4; ++q) { const int m = 2 * mp + (q >> 1), bj = q & 1; const int row = u.pm * 256 + ai * 128 + wr * 64 + m * 16 + fr, col = u.pn * 256 + bj * 128 + wc * 32 + 8 * fq;
;                     const pg8::f32x4 t0 = acc[ai][bj][m][0], t1 = acc[ai][bj][m][1];
;                     float v[8] = {t0[0], t0[1], t0[2], t0[3], t1[0], t1[1], t1[2], t1[3]};
;                     if constexpr (MODE == 5) {
; #pragma unroll
;                         for (int e = 0; e < 8; ++e) { const float r = fmaxf(v[e], 0.f); v[e] = r * r; }
;                     }
;                     if constexpr (MODE == 6) { const u32x4 g = gpre[q];
;                         v[0] *= sigmoidf_(bf_lo(g.x)); v[1] *= sigmoidf_(bf_hi(g.x)); v[2] *= sigmoidf_(bf_lo(g.y)); v[3] *= sigmoidf_(bf_hi(g.y));
;                         v[4] *= sigmoidf_(bf_lo(g.z)); v[5] *= sigmoidf_(bf_hi(g.z)); v[6] *= sigmoidf_(bf_lo(g.w)); v[7] *= sigmoidf_(bf_hi(g.w)); }
;                     u32x4 w; w.x = pkh(v[0], v[1]); w.y = pkh(v[2], v[3]); w.z = pkh(v[4], v[5]); w.w = pkh(v[6], v[7]);
;                     *(u32x4*)(ob + (size_t)row * LDC + col) = w; }
	v_lshlrev_b32_e32 v0, 16, v132
	v_pk_mul_f32 v[138:139], v[50:51], v[138:139]
	v_mul_f32_e32 v0, 0xbfb8aa3b, v0
	v_cvt_pk_bf16_f32 v145, v138, v139
	v_exp_f32_e32 v138, v0
	v_and_b32_e32 v0, 0xffff0000, v132
	v_mul_f32_e32 v0, 0xbfb8aa3b, v0
	v_exp_f32_e32 v139, v0
	v_ashrrev_i32_e32 v141, 31, v140
	v_lshlrev_b64 v[136:137], 12, v[140:141]
	v_lshl_add_u64 v[136:137], s[10:11], 0, v[136:137]
	v_pk_add_f32 v[138:139], v[138:139], 1.0 op_sel_hi:[1,0]
	v_lshl_add_u64 v[136:137], v[136:137], 0, v[2:3]
	v_div_scale_f32 v0, s[28:29], v139, v139, 1.0
	v_rcp_f32_e32 v132, v0
	global_store_dwordx4 v[136:137], v[142:145], off sc0 sc1
	v_fma_f32 v140, -v0, v132, 1.0
	v_fmac_f32_e32 v132, v140, v132
	v_div_scale_f32 v140, vcc, 1.0, v139, 1.0
	v_mul_f32_e32 v141, v140, v132
	v_fma_f32 v142, -v0, v141, v140
	v_fmac_f32_e32 v141, v142, v132
	v_fma_f32 v0, -v0, v141, v140
	v_div_fmas_f32 v0, v0, v132, v141
	v_div_fixup_f32 v139, v0, v139, 1.0
	v_div_scale_f32 v0, s[28:29], v138, v138, 1.0
	v_rcp_f32_e32 v132, v0
	s_nop 0
	v_fma_f32 v140, -v0, v132, 1.0
	v_fmac_f32_e32 v132, v140, v132
	v_div_scale_f32 v140, vcc, 1.0, v138, 1.0
	v_mul_f32_e32 v141, v140, v132
	v_fma_f32 v142, -v0, v141, v140
	v_fmac_f32_e32 v141, v142, v132
	v_fma_f32 v0, -v0, v141, v140
	v_div_fmas_f32 v0, v0, v132, v141
	v_div_fixup_f32 v138, v0, v138, 1.0
	v_lshlrev_b32_e32 v0, 16, v133
	v_mul_f32_e32 v0, 0xbfb8aa3b, v0
	v_exp_f32_e32 v132, v0
	v_and_b32_e32 v0, 0xffff0000, v133
	v_mul_f32_e32 v0, 0xbfb8aa3b, v0
	v_exp_f32_e32 v133, v0
	v_pk_mul_f32 v[138:139], v[68:69], v[138:139]
	v_pk_add_f32 v[132:133], v[132:133], 1.0 op_sel_hi:[1,0]
	s_nop 0
	v_div_scale_f32 v0, s[28:29], v133, v133, 1.0
	v_rcp_f32_e32 v140, v0
	s_nop 0
	v_fma_f32 v141, -v0, v140, 1.0
	v_fmac_f32_e32 v140, v141, v140
	v_div_scale_f32 v141, vcc, 1.0, v133, 1.0
	v_mul_f32_e32 v142, v141, v140
	v_fma_f32 v143, -v0, v142, v141
	v_fmac_f32_e32 v142, v143, v140
	v_fma_f32 v0, -v0, v142, v141
	v_div_fmas_f32 v0, v0, v140, v142
	v_div_fixup_f32 v133, v0, v133, 1.0
	v_div_scale_f32 v0, s[28:29], v132, v132, 1.0
	v_rcp_f32_e32 v140, v0
	s_nop 0
	v_fma_f32 v141, -v0, v140, 1.0
	v_fmac_f32_e32 v140, v141, v140
	v_div_scale_f32 v141, vcc, 1.0, v132, 1.0
	v_mul_f32_e32 v142, v141, v140
	v_fma_f32 v143, -v0, v142, v141
	v_fmac_f32_e32 v142, v143, v140
	v_fma_f32 v0, -v0, v142, v141
	v_div_fmas_f32 v0, v0, v140, v142
	v_div_fixup_f32 v132, v0, v132, 1.0
	v_lshlrev_b32_e32 v0, 16, v134
	v_mul_f32_e32 v0, 0xbfb8aa3b, v0
	v_pk_mul_f32 v[140:141], v[70:71], v[132:133]
	v_exp_f32_e32 v132, v0
	v_and_b32_e32 v0, 0xffff0000, v134
	v_mul_f32_e32 v0, 0xbfb8aa3b, v0
	v_exp_f32_e32 v133, v0
	s_nop 0
	v_pk_add_f32 v[132:133], v[132:133], 1.0 op_sel_hi:[1,0]
	s_nop 0
	v_div_scale_f32 v0, s[28:29], v133, v133, 1.0
	v_rcp_f32_e32 v134, v0
	s_nop 0
	v_fma_f32 v142, -v0, v134, 1.0
	v_fmac_f32_e32 v134, v142, v134
	v_div_scale_f32 v142, vcc, 1.0, v133, 1.0
	v_mul_f32_e32 v143, v142, v134
	v_fma_f32 v144, -v0, v143, v142
	v_fmac_f32_e32 v143, v144, v134
	v_fma_f32 v0, -v0, v143, v142
	v_div_fmas_f32 v0, v0, v134, v143
	v_div_fixup_f32 v133, v0, v133, 1.0
	v_div_scale_f32 v0, s[28:29], v132, v132, 1.0
	v_rcp_f32_e32 v134, v0
	s_nop 0
	v_fma_f32 v142, -v0, v134, 1.0
	v_fmac_f32_e32 v134, v142, v134
	v_div_scale_f32 v142, vcc, 1.0, v132, 1.0
	v_mul_f32_e32 v143, v142, v134
	v_fma_f32 v144, -v0, v143, v142
	v_fmac_f32_e32 v143, v144, v134
	v_fma_f32 v0, -v0, v143, v142
	v_div_fmas_f32 v0, v0, v134, v143
	v_div_fixup_f32 v132, v0, v132, 1.0
	v_lshlrev_b32_e32 v0, 16, v135
	v_mul_f32_e32 v0, 0xbfb8aa3b, v0
	v_pk_mul_f32 v[142:143], v[72:73], v[132:133]
	v_exp_f32_e32 v132, v0
	v_and_b32_e32 v0, 0xffff0000, v135
	v_mul_f32_e32 v0, 0xbfb8aa3b, v0
	v_exp_f32_e32 v133, v0
	s_nop 0
	v_pk_add_f32 v[132:133], v[132:133], 1.0 op_sel_hi:[1,0]
	s_nop 0
	v_div_scale_f32 v0, s[28:29], v133, v133, 1.0
	v_rcp_f32_e32 v134, v0
	s_nop 0
	v_fma_f32 v135, -v0, v134, 1.0
	v_fmac_f32_e32 v134, v135, v134
	v_div_scale_f32 v135, vcc, 1.0, v133, 1.0
	v_mul_f32_e32 v144, v135, v134
	v_fma_f32 v145, -v0, v144, v135
	v_fmac_f32_e32 v144, v145, v134
	v_fma_f32 v0, -v0, v144, v135
	v_div_fmas_f32 v0, v0, v134, v144
	v_div_fixup_f32 v133, v0, v133, 1.0
	v_div_scale_f32 v0, s[28:29], v132, v132, 1.0
	v_rcp_f32_e32 v134, v0
	s_nop 0
	v_fma_f32 v135, -v0, v134, 1.0
	v_fmac_f32_e32 v134, v135, v134
	v_div_scale_f32 v135, vcc, 1.0, v132, 1.0
	v_mul_f32_e32 v144, v135, v134
	v_fma_f32 v145, -v0, v144, v135
	v_fmac_f32_e32 v144, v145, v134
	v_fma_f32 v0, -v0, v144, v135
	v_div_fmas_f32 v0, v0, v134, v144
	v_div_fixup_f32 v132, v0, v132, 1.0
	v_pk_mul_f32 v[144:145], v[74:75], v[132:133]
	v_cvt_pk_bf16_f32 v132, v138, v139
	v_cvt_pk_bf16_f32 v133, v140, v141
	v_cvt_pk_bf16_f32 v134, v142, v143
	v_cvt_pk_bf16_f32 v135, v144, v145
	global_store_dwordx4 v[136:137], v[132:135], off offset:256 sc0 sc1
	s_nop 1
	v_mad_i64_i32 v[132:133], s[28:29], v156, s76, v[150:151]
	v_lshl_add_u64 v[132:133], v[132:133], 0, s[30:31]
	v_lshl_add_u64 v[134:135], v[132:133], 0, v[2:3]
	global_load_dwordx4 v[144:147], v[134:135], off
	v_lshl_add_u64 v[132:133], v[132:133], 0, v[152:153]
	global_load_dwordx4 v[140:143], v[132:133], off
	v_mad_i64_i32 v[132:133], s[28:29], v154, s76, v[150:151]
	v_lshl_add_u64 v[132:133], v[132:133], 0, s[30:31]
	v_lshl_add_u64 v[134:135], v[132:133], 0, v[2:3]
	global_load_dwordx4 v[136:139], v[134:135], off
	v_lshl_add_u64 v[132:133], v[132:133], 0, v[152:153]
	global_load_dwordx4 v[132:135], v[132:133], off
	s_waitcnt vmcnt(0)
; __device__ __forceinline__ unsigned pkh(float lo, float hi) { f32v2_t v; v.x = lo; v.y = hi; return __builtin_bit_cast(unsigned, __builtin_convertvector(v, bf16v2_t)); }
; __device__ __forceinline__ float bf_lo(unsigned w) { return __uint_as_float(w << 16); }
; __device__ __forceinline__ float bf_hi(unsigned w) { return __uint_as_float(w & 0xffff0000u); }
; __device__ __forceinline__ float sigmoidf_(float x) { return 1.0f / (1.0f + __expf(-x)); }
;     template <int MODE> __device__ __forceinline__ void run(const pg8::f32x4 (&acc)[2][2][4][2], const pg8::Unit& u, int wr, int wc, int fr, int fq) const {
;     ...
;                 if constexpr (MODE == 6) {
; #pragma unroll
;                     for (int q = 0; q < 4; ++q) { const int m = 2 * mp + (q >> 1), bj = q & 1; const int row = u.pm * 256 + ai * 128 + wr * 64 + m * 16 + fr, col = u.pn * 256 + bj * 128 + wc * 32 + 8 * fq;
;                         gpre[q] = *(const u32x4*)(proj + (size_t)row * NP + OFF_MG + 2 * DM + col); }
;                 }
; #pragma unroll
;                 for (int q = 0; q < 4; ++q) { const int m = 2 * mp + (q >> 1), bj = q & 1; const int row = u.pm * 256 + ai * 128 + wr * 64 + m * 16 + fr, col = u.pn * 256 + bj * 128 + wc * 32 + 8 * fq;
;                     const pg8::f32x4 t0 = acc[ai][bj][m][0], t1 = acc[ai][bj][m][1];
;                     float v[8] = {t0[0], t0[1], t0[2], t0[3], t1[0], t1[1], t1[2], t1[3]};
;                     if constexpr (MODE == 5) {
; #pragma unroll
;                         for (int e = 0; e < 8; ++e) { const float r = fmaxf(v[e], 0.f); v[e] = r * r; }
;                     }
;                     if constexpr (MODE == 6) { const u32x4 g = gpre[q];
;                         v[0] *= sigmoidf_(bf_lo(g.x)); v[1] *= sigmoidf_(bf_hi(g.x)); v[2] *= sigmoidf_(bf_lo(g.y)); v[3] *= sigmoidf_(bf_hi(g.y));
;                         v[4] *= sigmoidf_(bf_lo(g.z)); v[5] *= sigmoidf_(bf_hi(g.z)); v[6] *= sigmoidf_(bf_lo(g.w)); v[7] *= sigmoidf_(bf_hi(g.w)); }
;                     u32x4 w; w.x = pkh(v[0], v[1]); w.y = pkh(v[2], v[3]); w.z = pkh(v[4], v[5]); w.w = pkh(v[6], v[7]);
;                     *(u32x4*)(ob + (size_t)row * LDC + col) = w; }
	v_lshlrev_b32_e32 v0, 16, v144
	v_mul_f32_e32 v0, 0xbfb8aa3b, v0
	v_exp_f32_e32 v158, v0
	v_and_b32_e32 v0, 0xffff0000, v144
	v_mul_f32_e32 v0, 0xbfb8aa3b, v0
	v_exp_f32_e32 v159, v0
	s_nop 0
	v_pk_add_f32 v[158:159], v[158:159], 1.0 op_sel_hi:[1,0]
	s_nop 0
	v_div_scale_f32 v0, s[28:29], v159, v159, 1.0
	v_rcp_f32_e32 v144, v0
	s_nop 0
	v_fma_f32 v149, -v0, v144, 1.0
	v_fmac_f32_e32 v144, v149, v144
	v_div_scale_f32 v149, vcc, 1.0, v159, 1.0
	v_mul_f32_e32 v155, v149, v144
	v_fma_f32 v160, -v0, v155, v149
	v_fmac_f32_e32 v155, v160, v144
	v_fma_f32 v0, -v0, v155, v149
	v_div_fmas_f32 v0, v0, v144, v155
	v_div_fixup_f32 v159, v0, v159, 1.0
	v_div_scale_f32 v0, s[28:29], v158, v158, 1.0
	v_rcp_f32_e32 v144, v0
	s_nop 0
	v_fma_f32 v149, -v0, v144, 1.0
	v_fmac_f32_e32 v144, v149, v144
	v_div_scale_f32 v149, vcc, 1.0, v158, 1.0
	v_mul_f32_e32 v155, v149, v144
	v_fma_f32 v160, -v0, v155, v149
	v_fmac_f32_e32 v155, v160, v144
	v_fma_f32 v0, -v0, v155, v149
	v_div_fmas_f32 v0, v0, v144, v155
	v_div_fixup_f32 v158, v0, v158, 1.0
	v_lshlrev_b32_e32 v0, 16, v145
	v_mul_f32_e32 v0, 0xbfb8aa3b, v0
	v_exp_f32_e32 v144, v0
	v_and_b32_e32 v0, 0xffff0000, v145
	v_mul_f32_e32 v0, 0xbfb8aa3b, v0
	v_exp_f32_e32 v145, v0
	v_pk_mul_f32 v[158:159], v[60:61], v[158:159]
	v_pk_add_f32 v[144:145], v[144:145], 1.0 op_sel_hi:[1,0]
	s_nop 0
	v_div_scale_f32 v0, s[28:29], v145, v145, 1.0
	v_rcp_f32_e32 v149, v0
	v_cvt_pk_bf16_f32 v158, v158, v159
	v_fma_f32 v155, -v0, v149, 1.0
	v_fmac_f32_e32 v149, v155, v149
	v_div_scale_f32 v155, vcc, 1.0, v145, 1.0
	v_mul_f32_e32 v160, v155, v149
	v_fma_f32 v161, -v0, v160, v155
	v_fmac_f32_e32 v160, v161, v149
	v_fma_f32 v0, -v0, v160, v155
	v_div_fmas_f32 v0, v0, v149, v160
	v_div_fixup_f32 v145, v0, v145, 1.0
	v_div_scale_f32 v0, s[28:29], v144, v144, 1.0
	v_rcp_f32_e32 v149, v0
	s_nop 0
	v_fma_f32 v155, -v0, v149, 1.0
	v_fmac_f32_e32 v149, v155, v149
	v_div_scale_f32 v155, vcc, 1.0, v144, 1.0
	v_mul_f32_e32 v160, v155, v149
	v_fma_f32 v161, -v0, v160, v155
	v_fmac_f32_e32 v160, v161, v149
	v_fma_f32 v0, -v0, v160, v155
	v_div_fmas_f32 v0, v0, v149, v160
	v_div_fixup_f32 v144, v0, v144, 1.0
	v_lshlrev_b32_e32 v0, 16, v146
	v_mul_f32_e32 v0, 0xbfb8aa3b, v0
	v_exp_f32_e32 v160, v0
	v_and_b32_e32 v0, 0xffff0000, v146
	v_mul_f32_e32 v0, 0xbfb8aa3b, v0
	v_exp_f32_e32 v161, v0
	v_pk_mul_f32 v[144:145], v[62:63], v[144:145]
	v_pk_add_f32 v[160:161], v[160:161], 1.0 op_sel_hi:[1,0]
	s_nop 0
	v_div_scale_f32 v0, s[28:29], v161, v161, 1.0
	v_rcp_f32_e32 v146, v0
	v_cvt_pk_bf16_f32 v159, v144, v145
	v_lshlrev_b64 v[144:145], 12, v[156:157]
	v_lshl_add_u64 v[144:145], s[10:11], 0, v[144:145]
	v_fma_f32 v149, -v0, v146, 1.0
	v_fmac_f32_e32 v146, v149, v146
	v_div_scale_f32 v149, vcc, 1.0, v161, 1.0
	v_mul_f32_e32 v155, v149, v146
	v_fma_f32 v162, -v0, v155, v149
	v_fmac_f32_e32 v155, v162, v146
	v_fma_f32 v0, -v0, v155, v149
	v_div_fmas_f32 v0, v0, v146, v155
	v_div_fixup_f32 v161, v0, v161, 1.0
	v_div_scale_f32 v0, s[28:29], v160, v160, 1.0
	v_rcp_f32_e32 v146, v0
	v_lshl_add_u64 v[144:145], v[144:145], 0, v[2:3]
	v_fma_f32 v149, -v0, v146, 1.0
	v_fmac_f32_e32 v146, v149, v146
	v_div_scale_f32 v149, vcc, 1.0, v160, 1.0
	v_mul_f32_e32 v155, v149, v146
	v_fma_f32 v162, -v0, v155, v149
	v_fmac_f32_e32 v155, v162, v146
	v_fma_f32 v0, -v0, v155, v149
	v_div_fmas_f32 v0, v0, v146, v155
	v_div_fixup_f32 v160, v0, v160, 1.0
	v_lshlrev_b32_e32 v0, 16, v147
	v_mul_f32_e32 v0, 0xbfb8aa3b, v0
	v_exp_f32_e32 v146, v0
	v_and_b32_e32 v0, 0xffff0000, v147
	v_mul_f32_e32 v0, 0xbfb8aa3b, v0
	v_exp_f32_e32 v147, v0
	v_pk_mul_f32 v[160:161], v[64:65], v[160:161]
	v_pk_add_f32 v[146:147], v[146:147], 1.0 op_sel_hi:[1,0]
	s_nop 0
	v_div_scale_f32 v0, s[28:29], v147, v147, 1.0
	v_rcp_f32_e32 v149, v0
	v_cvt_pk_bf16_f32 v160, v160, v161
	v_fma_f32 v155, -v0, v149, 1.0
	v_fmac_f32_e32 v149, v155, v149
	v_div_scale_f32 v155, vcc, 1.0, v147, 1.0
	v_mul_f32_e32 v162, v155, v149
	v_fma_f32 v163, -v0, v162, v155
	v_fmac_f32_e32 v162, v163, v149
	v_fma_f32 v0, -v0, v162, v155
	v_div_fmas_f32 v0, v0, v149, v162
	v_div_fixup_f32 v147, v0, v147, 1.0
	v_div_scale_f32 v0, s[28:29], v146, v146, 1.0
	v_rcp_f32_e32 v149, v0
	s_nop 0
	v_fma_f32 v155, -v0, v149, 1.0
	v_fmac_f32_e32 v149, v155, v149
	v_div_scale_f32 v155, vcc, 1.0, v146, 1.0
	v_mul_f32_e32 v162, v155, v149
	v_fma_f32 v163, -v0, v162, v155
	v_fmac_f32_e32 v162, v163, v149
	v_fma_f32 v0, -v0, v162, v155
	v_div_fmas_f32 v0, v0, v149, v162
	v_div_fixup_f32 v146, v0, v146, 1.0
	v_lshlrev_b32_e32 v0, 16, v140
	v_pk_mul_f32 v[146:147], v[66:67], v[146:147]
	v_mul_f32_e32 v0, 0xbfb8aa3b, v0
	v_cvt_pk_bf16_f32 v161, v146, v147
	v_exp_f32_e32 v146, v0
	v_and_b32_e32 v0, 0xffff0000, v140
	v_mul_f32_e32 v0, 0xbfb8aa3b, v0
	v_exp_f32_e32 v147, v0
	global_store_dwordx4 v[144:145], v[158:161], off sc0 sc1
	v_pk_add_f32 v[146:147], v[146:147], 1.0 op_sel_hi:[1,0]
	s_nop 0
	v_div_scale_f32 v0, s[28:29], v147, v147, 1.0
	v_rcp_f32_e32 v140, v0
	s_nop 0
	v_fma_f32 v149, -v0, v140, 1.0
	v_fmac_f32_e32 v140, v149, v140
	v_div_scale_f32 v149, vcc, 1.0, v147, 1.0
	v_mul_f32_e32 v155, v149, v140
	v_fma_f32 v156, -v0, v155, v149
	v_fmac_f32_e32 v155, v156, v140
	v_fma_f32 v0, -v0, v155, v149
	v_div_fmas_f32 v0, v0, v140, v155
	v_div_fixup_f32 v147, v0, v147, 1.0
	v_div_scale_f32 v0, s[28:29], v146, v146, 1.0
	v_rcp_f32_e32 v140, v0
	s_nop 0
	v_fma_f32 v149, -v0, v140, 1.0
	v_fmac_f32_e32 v140, v149, v140
	v_div_scale_f32 v149, vcc, 1.0, v146, 1.0
	v_mul_f32_e32 v155, v149, v140
	v_fma_f32 v156, -v0, v155, v149
	v_fmac_f32_e32 v155, v156, v140
	v_fma_f32 v0, -v0, v155, v149
	v_div_fmas_f32 v0, v0, v140, v155
	v_div_fixup_f32 v146, v0, v146, 1.0
; __device__ __forceinline__ unsigned pkh(float lo, float hi) { f32v2_t v; v.x = lo; v.y = hi; return __builtin_bit_cast(unsigned, __builtin_convertvector(v, bf16v2_t)); }
; __device__ __forceinline__ float bf_lo(unsigned w) { return __uint_as_float(w << 16); }
; __device__ __forceinline__ float bf_hi(unsigned w) { return __uint_as_float(w & 0xffff0000u); }
; __device__ __forceinline__ float sigmoidf_(float x) { return 1.0f / (1.0f + __expf(-x)); }
;     template <int MODE> __device__ __forceinline__ void run(const pg8::f32x4 (&acc)[2][2][4][2], const pg8::Unit& u, int wr, int wc, int fr, int fq) const {
;     ...
;                 if constexpr (MODE == 6) {
; #pragma unroll
;                     for (int q = 0; q < 4; ++q) { const int m = 2 * mp + (q >> 1), bj = q & 1; const int row = u.pm * 256 + ai * 128 + wr * 64 + m * 16 + fr, col = u.pn * 256 + bj * 128 + wc * 32 + 8 * fq;
;                         gpre[q] = *(const u32x4*)(proj + (size_t)row * NP + OFF_MG + 2 * DM + col); }
;                 }
; #pragma unroll
;                 for (int q = 0; q < 4; ++q) { const int m = 2 * mp + (q >> 1), bj = q & 1; const int row = u.pm * 256 + ai * 128 + wr * 64 + m * 16 + fr, col = u.pn * 256 + bj * 128 + wc * 32 + 8 * fq;
;                     const pg8::f32x4 t0 = acc[ai][bj][m][0], t1 = acc[ai][bj][m][1];
;                     float v[8] = {t0[0], t0[1], t0[2], t0[3], t1[0], t1[1], t1[2], t1[3]};
;                     if constexpr (MODE == 5) {
; #pragma unroll
;                         for (int e = 0; e < 8; ++e) { const float r = fmaxf(v[e], 0.f); v[e] = r * r; }
;                     }
;                     if constexpr (MODE == 6) { const u32x4 g = gpre[q];
;                         v[0] *= sigmoidf_(bf_lo(g.x)); v[1] *= sigmoidf_(bf_hi(g.x)); v[2] *= sigmoidf_(bf_lo(g.y)); v[3] *= sigmoidf_(bf_hi(g.y));
;                         v[4] *= sigmoidf_(bf_lo(g.z)); v[5] *= sigmoidf_(bf_hi(g.z)); v[6] *= sigmoidf_(bf_lo(g.w)); v[7] *= sigmoidf_(bf_hi(g.w)); }
;                     u32x4 w; w.x = pkh(v[0], v[1]); w.y = pkh(v[2], v[3]); w.z = pkh(v[4], v[5]); w.w = pkh(v[6], v[7]);
;                     *(u32x4*)(ob + (size_t)row * LDC + col) = w; }
	v_lshlrev_b32_e32 v0, 16, v141
	v_mul_f32_e32 v0, 0xbfb8aa3b, v0
	v_exp_f32_e32 v140, v0
	v_and_b32_e32 v0, 0xffff0000, v141
	v_mul_f32_e32 v0, 0xbfb8aa3b, v0
	v_exp_f32_e32 v141, v0
	v_pk_mul_f32 v[146:147], v[84:85], v[146:147]
	v_pk_add_f32 v[140:141], v[140:141], 1.0 op_sel_hi:[1,0]
	s_nop 0
	v_div_scale_f32 v0, s[28:29], v141, v141, 1.0
	v_rcp_f32_e32 v149, v0
	s_nop 0
	v_fma_f32 v155, -v0, v149, 1.0
	v_fmac_f32_e32 v149, v155, v149
	v_div_scale_f32 v155, vcc, 1.0, v141, 1.0
	v_mul_f32_e32 v156, v155, v149
	v_fma_f32 v157, -v0, v156, v155
	v_fmac_f32_e32 v156, v157, v149
	v_fma_f32 v0, -v0, v156, v155
	v_div_fmas_f32 v0, v0, v149, v156
	v_div_fixup_f32 v141, v0, v141, 1.0
	v_div_scale_f32 v0, s[28:29], v140, v140, 1.0
	v_rcp_f32_e32 v149, v0
	s_nop 0
	v_fma_f32 v155, -v0, v149, 1.0
	v_fmac_f32_e32 v149, v155, v149
	v_div_scale_f32 v155, vcc, 1.0, v140, 1.0
	v_mul_f32_e32 v156, v155, v149
	v_fma_f32 v157, -v0, v156, v155
	v_fmac_f32_e32 v156, v157, v149
	v_fma_f32 v0, -v0, v156, v155
	v_div_fmas_f32 v0, v0, v149, v156
	v_div_fixup_f32 v140, v0, v140, 1.0
	v_lshlrev_b32_e32 v0, 16, v142
	v_mul_f32_e32 v0, 0xbfb8aa3b, v0
	v_pk_mul_f32 v[156:157], v[86:87], v[140:141]
	v_exp_f32_e32 v140, v0
	v_and_b32_e32 v0, 0xffff0000, v142
	v_mul_f32_e32 v0, 0xbfb8aa3b, v0
	v_exp_f32_e32 v141, v0
	s_nop 0
	v_pk_add_f32 v[140:141], v[140:141], 1.0 op_sel_hi:[1,0]
	s_nop 0
	v_div_scale_f32 v0, s[28:29], v141, v141, 1.0
	v_rcp_f32_e32 v142, v0
	s_nop 0
	v_fma_f32 v149, -v0, v142, 1.0
	v_fmac_f32_e32 v142, v149, v142
	v_div_scale_f32 v149, vcc, 1.0, v141, 1.0
	v_mul_f32_e32 v155, v149, v142
	v_fma_f32 v158, -v0, v155, v149
	v_fmac_f32_e32 v155, v158, v142
	v_fma_f32 v0, -v0, v155, v149
	v_div_fmas_f32 v0, v0, v142, v155
	v_div_fixup_f32 v141, v0, v141, 1.0
	v_div_scale_f32 v0, s[28:29], v140, v140, 1.0
	v_rcp_f32_e32 v142, v0
	s_nop 0
	v_fma_f32 v149, -v0, v142, 1.0
	v_fmac_f32_e32 v142, v149, v142
	v_div_scale_f32 v149, vcc, 1.0, v140, 1.0
	v_mul_f32_e32 v155, v149, v142
	v_fma_f32 v158, -v0, v155, v149
	v_fmac_f32_e32 v155, v158, v142
	v_fma_f32 v0, -v0, v155, v149
	v_div_fmas_f32 v0, v0, v142, v155
	v_div_fixup_f32 v140, v0, v140, 1.0
	v_lshlrev_b32_e32 v0, 16, v143
	v_mul_f32_e32 v0, 0xbfb8aa3b, v0
	v_pk_mul_f32 v[158:159], v[88:89], v[140:141]
	v_exp_f32_e32 v140, v0
	v_and_b32_e32 v0, 0xffff0000, v143
	v_mul_f32_e32 v0, 0xbfb8aa3b, v0
	v_exp_f32_e32 v141, v0
	s_nop 0
	v_pk_add_f32 v[140:141], v[140:141], 1.0 op_sel_hi:[1,0]
	s_nop 0
	v_div_scale_f32 v0, s[28:29], v141, v141, 1.0
	v_rcp_f32_e32 v142, v0
	s_nop 0
	v_fma_f32 v143, -v0, v142, 1.0
	v_fmac_f32_e32 v142, v143, v142
	v_div_scale_f32 v143, vcc, 1.0, v141, 1.0
	v_mul_f32_e32 v149, v143, v142
	v_fma_f32 v155, -v0, v149, v143
	v_fmac_f32_e32 v149, v155, v142
	v_fma_f32 v0, -v0, v149, v143
	v_div_fmas_f32 v0, v0, v142, v149
	v_div_fixup_f32 v141, v0, v141, 1.0
	v_div_scale_f32 v0, s[28:29], v140, v140, 1.0
	v_rcp_f32_e32 v142, v0
	s_nop 0
	v_fma_f32 v143, -v0, v142, 1.0
	v_fmac_f32_e32 v142, v143, v142
	v_div_scale_f32 v143, vcc, 1.0, v140, 1.0
	v_mul_f32_e32 v149, v143, v142
	v_fma_f32 v155, -v0, v149, v143
	v_fmac_f32_e32 v149, v155, v142
	v_fma_f32 v0, -v0, v149, v143
	v_div_fmas_f32 v0, v0, v142, v149
	v_div_fixup_f32 v140, v0, v140, 1.0
	v_pk_mul_f32 v[160:161], v[90:91], v[140:141]
	v_lshlrev_b32_e32 v0, 16, v136
	v_cvt_pk_bf16_f32 v140, v146, v147
	v_cvt_pk_bf16_f32 v141, v156, v157
	v_cvt_pk_bf16_f32 v142, v158, v159
	v_cvt_pk_bf16_f32 v143, v160, v161
	v_mul_f32_e32 v0, 0xbfb8aa3b, v0
	global_store_dwordx4 v[144:145], v[140:143], off offset:256 sc0 sc1
	v_ashrrev_i32_e32 v155, 31, v154
	s_nop 0
	v_exp_f32_e32 v140, v0
	v_and_b32_e32 v0, 0xffff0000, v136
	v_mul_f32_e32 v0, 0xbfb8aa3b, v0
	v_exp_f32_e32 v141, v0
	s_nop 0
	v_pk_add_f32 v[140:141], v[140:141], 1.0 op_sel_hi:[1,0]
	s_nop 0
	v_div_scale_f32 v0, s[28:29], v141, v141, 1.0
	v_rcp_f32_e32 v136, v0
	s_nop 0
	v_fma_f32 v142, -v0, v136, 1.0
	v_fmac_f32_e32 v136, v142, v136
	v_div_scale_f32 v142, vcc, 1.0, v141, 1.0
	v_mul_f32_e32 v143, v142, v136
	v_fma_f32 v144, -v0, v143, v142
	v_fmac_f32_e32 v143, v144, v136
	v_fma_f32 v0, -v0, v143, v142
	v_div_fmas_f32 v0, v0, v136, v143
	v_div_fixup_f32 v141, v0, v141, 1.0
	v_div_scale_f32 v0, s[28:29], v140, v140, 1.0
	v_rcp_f32_e32 v136, v0
	s_nop 0
	v_fma_f32 v142, -v0, v136, 1.0
	v_fmac_f32_e32 v136, v142, v136
	v_div_scale_f32 v142, vcc, 1.0, v140, 1.0
	v_mul_f32_e32 v143, v142, v136
	v_fma_f32 v144, -v0, v143, v142
	v_fmac_f32_e32 v143, v144, v136
	v_fma_f32 v0, -v0, v143, v142
	v_div_fmas_f32 v0, v0, v136, v143
	v_div_fixup_f32 v140, v0, v140, 1.0
	v_lshlrev_b32_e32 v0, 16, v137
	v_mul_f32_e32 v0, 0xbfb8aa3b, v0
	v_exp_f32_e32 v136, v0
	v_and_b32_e32 v0, 0xffff0000, v137
	v_mul_f32_e32 v0, 0xbfb8aa3b, v0
	v_exp_f32_e32 v137, v0
	v_pk_mul_f32 v[140:141], v[36:37], v[140:141]
	v_pk_add_f32 v[136:137], v[136:137], 1.0 op_sel_hi:[1,0]
	s_nop 0
	v_div_scale_f32 v0, s[28:29], v137, v137, 1.0
	v_rcp_f32_e32 v142, v0
	s_nop 0
	v_fma_f32 v143, -v0, v142, 1.0
	v_fmac_f32_e32 v142, v143, v142
	v_div_scale_f32 v143, vcc, 1.0, v137, 1.0
	v_mul_f32_e32 v144, v143, v142
	v_fma_f32 v145, -v0, v144, v143
	v_fmac_f32_e32 v144, v145, v142
	v_fma_f32 v0, -v0, v144, v143
	v_div_fmas_f32 v0, v0, v142, v144
	v_div_fixup_f32 v137, v0, v137, 1.0
	v_div_scale_f32 v0, s[28:29], v136, v136, 1.0
	v_rcp_f32_e32 v142, v0
	s_nop 0
	v_fma_f32 v143, -v0, v142, 1.0
	v_fmac_f32_e32 v142, v143, v142
	v_div_scale_f32 v143, vcc, 1.0, v136, 1.0
	v_mul_f32_e32 v144, v143, v142
	v_fma_f32 v145, -v0, v144, v143
	v_fmac_f32_e32 v144, v145, v142
	v_fma_f32 v0, -v0, v144, v143
	v_div_fmas_f32 v0, v0, v142, v144
; __device__ __forceinline__ unsigned pkh(float lo, float hi) { f32v2_t v; v.x = lo; v.y = hi; return __builtin_bit_cast(unsigned, __builtin_convertvector(v, bf16v2_t)); }
; __device__ __forceinline__ float bf_lo(unsigned w) { return __uint_as_float(w << 16); }
; __device__ __forceinline__ float bf_hi(unsigned w) { return __uint_as_float(w & 0xffff0000u); }
; __device__ __forceinline__ float sigmoidf_(float x) { return 1.0f / (1.0f + __expf(-x)); }
;     template <int MODE> __device__ __forceinline__ void run(const pg8::f32x4 (&acc)[2][2][4][2], const pg8::Unit& u, int wr, int wc, int fr, int fq) const {
;     ...
;                 if constexpr (MODE == 6) {
; #pragma unroll
;                     for (int q = 0; q < 4; ++q) { const int m = 2 * mp + (q >> 1), bj = q & 1; const int row = u.pm * 256 + ai * 128 + wr * 64 + m * 16 + fr, col = u.pn * 256 + bj * 128 + wc * 32 + 8 * fq;
;                         gpre[q] = *(const u32x4*)(proj + (size_t)row * NP + OFF_MG + 2 * DM + col); }
;                 }
; #pragma unroll
;                 for (int q = 0; q < 4; ++q) { const int m = 2 * mp + (q >> 1), bj = q & 1; const int row = u.pm * 256 + ai * 128 + wr * 64 + m * 16 + fr, col = u.pn * 256 + bj * 128 + wc * 32 + 8 * fq;
;                     const pg8::f32x4 t0 = acc[ai][bj][m][0], t1 = acc[ai][bj][m][1];
;                     float v[8] = {t0[0], t0[1], t0[2], t0[3], t1[0], t1[1], t1[2], t1[3]};
;                     if constexpr (MODE == 5) {
; #pragma unroll
;                         for (int e = 0; e < 8; ++e) { const float r = fmaxf(v[e], 0.f); v[e] = r * r; }
;                     }
;                     if constexpr (MODE == 6) { const u32x4 g = gpre[q];
;                         v[0] *= sigmoidf_(bf_lo(g.x)); v[1] *= sigmoidf_(bf_hi(g.x)); v[2] *= sigmoidf_(bf_lo(g.y)); v[3] *= sigmoidf_(bf_hi(g.y));
;                         v[4] *= sigmoidf_(bf_lo(g.z)); v[5] *= sigmoidf_(bf_hi(g.z)); v[6] *= sigmoidf_(bf_lo(g.w)); v[7] *= sigmoidf_(bf_hi(g.w)); }
;                     u32x4 w; w.x = pkh(v[0], v[1]); w.y = pkh(v[2], v[3]); w.z = pkh(v[4], v[5]); w.w = pkh(v[6], v[7]);
;                     *(u32x4*)(ob + (size_t)row * LDC + col) = w; }
	v_div_fixup_f32 v136, v0, v136, 1.0
	v_lshlrev_b32_e32 v0, 16, v138
	v_mul_f32_e32 v0, 0xbfb8aa3b, v0
	v_exp_f32_e32 v142, v0
	v_and_b32_e32 v0, 0xffff0000, v138
	v_mul_f32_e32 v0, 0xbfb8aa3b, v0
	v_exp_f32_e32 v143, v0
	v_pk_mul_f32 v[136:137], v[38:39], v[136:137]
	v_pk_add_f32 v[142:143], v[142:143], 1.0 op_sel_hi:[1,0]
	s_nop 0
	v_div_scale_f32 v0, s[28:29], v143, v143, 1.0
	v_rcp_f32_e32 v138, v0
	s_nop 0
	v_fma_f32 v144, -v0, v138, 1.0
	v_fmac_f32_e32 v138, v144, v138
	v_div_scale_f32 v144, vcc, 1.0, v143, 1.0
	v_mul_f32_e32 v145, v144, v138
	v_fma_f32 v146, -v0, v145, v144
	v_fmac_f32_e32 v145, v146, v138
	v_fma_f32 v0, -v0, v145, v144
	v_div_fmas_f32 v0, v0, v138, v145
	v_div_fixup_f32 v143, v0, v143, 1.0
	v_div_scale_f32 v0, s[28:29], v142, v142, 1.0
	v_rcp_f32_e32 v138, v0
	s_nop 0
	v_fma_f32 v144, -v0, v138, 1.0
	v_fmac_f32_e32 v138, v144, v138
	v_div_scale_f32 v144, vcc, 1.0, v142, 1.0
	v_mul_f32_e32 v145, v144, v138
	v_fma_f32 v146, -v0, v145, v144
	v_fmac_f32_e32 v145, v146, v138
	v_fma_f32 v0, -v0, v145, v144
	v_div_fmas_f32 v0, v0, v138, v145
	v_div_fixup_f32 v142, v0, v142, 1.0
	v_lshlrev_b32_e32 v0, 16, v139
	v_mul_f32_e32 v0, 0xbfb8aa3b, v0
	v_exp_f32_e32 v138, v0
	v_and_b32_e32 v0, 0xffff0000, v139
	v_mul_f32_e32 v0, 0xbfb8aa3b, v0
	v_exp_f32_e32 v139, v0
	v_pk_mul_f32 v[142:143], v[40:41], v[142:143]
	v_pk_add_f32 v[138:139], v[138:139], 1.0 op_sel_hi:[1,0]
	s_nop 0
	v_div_scale_f32 v0, s[28:29], v139, v139, 1.0
	v_rcp_f32_e32 v144, v0
	s_nop 0
	v_fma_f32 v145, -v0, v144, 1.0
	v_fmac_f32_e32 v144, v145, v144
	v_div_scale_f32 v145, vcc, 1.0, v139, 1.0
	v_mul_f32_e32 v146, v145, v144
	v_fma_f32 v147, -v0, v146, v145
	v_fmac_f32_e32 v146, v147, v144
	v_fma_f32 v0, -v0, v146, v145
	v_div_fmas_f32 v0, v0, v144, v146
	v_div_fixup_f32 v139, v0, v139, 1.0
	v_div_scale_f32 v0, s[28:29], v138, v138, 1.0
	v_rcp_f32_e32 v144, v0
	s_nop 0
	v_fma_f32 v145, -v0, v144, 1.0
	v_fmac_f32_e32 v144, v145, v144
	v_div_scale_f32 v145, vcc, 1.0, v138, 1.0
	v_mul_f32_e32 v146, v145, v144
	v_fma_f32 v147, -v0, v146, v145
	v_fmac_f32_e32 v146, v147, v144
	v_fma_f32 v0, -v0, v146, v145
	v_div_fmas_f32 v0, v0, v144, v146
	v_div_fixup_f32 v138, v0, v138, 1.0
	v_pk_mul_f32 v[144:145], v[42:43], v[138:139]
	v_cvt_pk_bf16_f32 v139, v136, v137
	v_lshlrev_b64 v[136:137], 12, v[154:155]
	v_lshl_add_u64 v[136:137], s[10:11], 0, v[136:137]
	v_lshlrev_b32_e32 v0, 16, v132
	v_cvt_pk_bf16_f32 v138, v140, v141
	v_cvt_pk_bf16_f32 v140, v142, v143
	v_cvt_pk_bf16_f32 v141, v144, v145
	v_lshl_add_u64 v[136:137], v[136:137], 0, v[2:3]
	v_mul_f32_e32 v0, 0xbfb8aa3b, v0
	global_store_dwordx4 v[136:137], v[138:141], off sc0 sc1
	v_add_u32_e32 v154, 0xa0, v148
	v_add_u32_e32 v148, 0xb0, v148
	v_exp_f32_e32 v138, v0
	v_and_b32_e32 v0, 0xffff0000, v132
	v_mul_f32_e32 v0, 0xbfb8aa3b, v0
	v_exp_f32_e32 v139, v0
	v_ashrrev_i32_e32 v155, 31, v154
	v_pk_add_f32 v[138:139], v[138:139], 1.0 op_sel_hi:[1,0]
	s_nop 0
	v_div_scale_f32 v0, s[28:29], v139, v139, 1.0
	v_rcp_f32_e32 v132, v0
	s_nop 0
	v_fma_f32 v140, -v0, v132, 1.0
	v_fmac_f32_e32 v132, v140, v132
	v_div_scale_f32 v140, vcc, 1.0, v139, 1.0
	v_mul_f32_e32 v141, v140, v132
	v_fma_f32 v142, -v0, v141, v140
	v_fmac_f32_e32 v141, v142, v132
	v_fma_f32 v0, -v0, v141, v140
	v_div_fmas_f32 v0, v0, v132, v141
	v_div_fixup_f32 v139, v0, v139, 1.0
	v_div_scale_f32 v0, s[28:29], v138, v138, 1.0
	v_rcp_f32_e32 v132, v0
	s_nop 0
	v_fma_f32 v140, -v0, v132, 1.0
	v_fmac_f32_e32 v132, v140, v132
	v_div_scale_f32 v140, vcc, 1.0, v138, 1.0
	v_mul_f32_e32 v141, v140, v132
	v_fma_f32 v142, -v0, v141, v140
	v_fmac_f32_e32 v141, v142, v132
	v_fma_f32 v0, -v0, v141, v140
	v_div_fmas_f32 v0, v0, v132, v141
	v_div_fixup_f32 v138, v0, v138, 1.0
	v_lshlrev_b32_e32 v0, 16, v133
	v_mul_f32_e32 v0, 0xbfb8aa3b, v0
	v_exp_f32_e32 v132, v0
	v_and_b32_e32 v0, 0xffff0000, v133
	v_mul_f32_e32 v0, 0xbfb8aa3b, v0
	v_exp_f32_e32 v133, v0
	v_pk_mul_f32 v[138:139], v[52:53], v[138:139]
	v_pk_add_f32 v[132:133], v[132:133], 1.0 op_sel_hi:[1,0]
	s_nop 0
	v_div_scale_f32 v0, s[28:29], v133, v133, 1.0
	v_rcp_f32_e32 v140, v0
	s_nop 0
	v_fma_f32 v141, -v0, v140, 1.0
	v_fmac_f32_e32 v140, v141, v140
	v_div_scale_f32 v141, vcc, 1.0, v133, 1.0
	v_mul_f32_e32 v142, v141, v140
	v_fma_f32 v143, -v0, v142, v141
	v_fmac_f32_e32 v142, v143, v140
	v_fma_f32 v0, -v0, v142, v141
	v_div_fmas_f32 v0, v0, v140, v142
	v_div_fixup_f32 v133, v0, v133, 1.0
	v_div_scale_f32 v0, s[28:29], v132, v132, 1.0
	v_rcp_f32_e32 v140, v0
	s_nop 0
	v_fma_f32 v141, -v0, v140, 1.0
	v_fmac_f32_e32 v140, v141, v140
	v_div_scale_f32 v141, vcc, 1.0, v132, 1.0
	v_mul_f32_e32 v142, v141, v140
	v_fma_f32 v143, -v0, v142, v141
	v_fmac_f32_e32 v142, v143, v140
	v_fma_f32 v0, -v0, v142, v141
	v_div_fmas_f32 v0, v0, v140, v142
	v_div_fixup_f32 v132, v0, v132, 1.0
	v_lshlrev_b32_e32 v0, 16, v134
	v_mul_f32_e32 v0, 0xbfb8aa3b, v0
	v_pk_mul_f32 v[140:141], v[54:55], v[132:133]
	v_exp_f32_e32 v132, v0
	v_and_b32_e32 v0, 0xffff0000, v134
	v_mul_f32_e32 v0, 0xbfb8aa3b, v0
	v_exp_f32_e32 v133, v0
	s_nop 0
	v_pk_add_f32 v[132:133], v[132:133], 1.0 op_sel_hi:[1,0]
	s_nop 0
	v_div_scale_f32 v0, s[28:29], v133, v133, 1.0
	v_rcp_f32_e32 v134, v0
	s_nop 0
	v_fma_f32 v142, -v0, v134, 1.0
	v_fmac_f32_e32 v134, v142, v134
	v_div_scale_f32 v142, vcc, 1.0, v133, 1.0
	v_mul_f32_e32 v143, v142, v134
	v_fma_f32 v144, -v0, v143, v142
	v_fmac_f32_e32 v143, v144, v134
	v_fma_f32 v0, -v0, v143, v142
	v_div_fmas_f32 v0, v0, v134, v143
	v_div_fixup_f32 v133, v0, v133, 1.0
	v_div_scale_f32 v0, s[28:29], v132, v132, 1.0
	v_rcp_f32_e32 v134, v0
	s_nop 0
	v_fma_f32 v142, -v0, v134, 1.0
	v_fmac_f32_e32 v134, v142, v134
; __device__ __forceinline__ unsigned pkh(float lo, float hi) { f32v2_t v; v.x = lo; v.y = hi; return __builtin_bit_cast(unsigned, __builtin_convertvector(v, bf16v2_t)); }
; __device__ __forceinline__ float bf_lo(unsigned w) { return __uint_as_float(w << 16); }
; __device__ __forceinline__ float bf_hi(unsigned w) { return __uint_as_float(w & 0xffff0000u); }
; __device__ __forceinline__ float sigmoidf_(float x) { return 1.0f / (1.0f + __expf(-x)); }
;     template <int MODE> __device__ __forceinline__ void run(const pg8::f32x4 (&acc)[2][2][4][2], const pg8::Unit& u, int wr, int wc, int fr, int fq) const {
;     ...
;                 if constexpr (MODE == 6) {
; #pragma unroll
;                     for (int q = 0; q < 4; ++q) { const int m = 2 * mp + (q >> 1), bj = q & 1; const int row = u.pm * 256 + ai * 128 + wr * 64 + m * 16 + fr, col = u.pn * 256 + bj * 128 + wc * 32 + 8 * fq;
;                         gpre[q] = *(const u32x4*)(proj + (size_t)row * NP + OFF_MG + 2 * DM + col); }
;                 }
; #pragma unroll
;                 for (int q = 0; q < 4; ++q) { const int m = 2 * mp + (q >> 1), bj = q & 1; const int row = u.pm * 256 + ai * 128 + wr * 64 + m * 16 + fr, col = u.pn * 256 + bj * 128 + wc * 32 + 8 * fq;
;                     const pg8::f32x4 t0 = acc[ai][bj][m][0], t1 = acc[ai][bj][m][1];
;                     float v[8] = {t0[0], t0[1], t0[2], t0[3], t1[0], t1[1], t1[2], t1[3]};
;                     if constexpr (MODE == 5) {
; #pragma unroll
;                         for (int e = 0; e < 8; ++e) { const float r = fmaxf(v[e], 0.f); v[e] = r * r; }
;                     }
;                     if constexpr (MODE == 6) { const u32x4 g = gpre[q];
;                         v[0] *= sigmoidf_(bf_lo(g.x)); v[1] *= sigmoidf_(bf_hi(g.x)); v[2] *= sigmoidf_(bf_lo(g.y)); v[3] *= sigmoidf_(bf_hi(g.y));
;                         v[4] *= sigmoidf_(bf_lo(g.z)); v[5] *= sigmoidf_(bf_hi(g.z)); v[6] *= sigmoidf_(bf_lo(g.w)); v[7] *= sigmoidf_(bf_hi(g.w)); }
;                     u32x4 w; w.x = pkh(v[0], v[1]); w.y = pkh(v[2], v[3]); w.z = pkh(v[4], v[5]); w.w = pkh(v[6], v[7]);
;                     *(u32x4*)(ob + (size_t)row * LDC + col) = w; }
	v_div_scale_f32 v142, vcc, 1.0, v132, 1.0
	v_mul_f32_e32 v143, v142, v134
	v_fma_f32 v144, -v0, v143, v142
	v_fmac_f32_e32 v143, v144, v134
	v_fma_f32 v0, -v0, v143, v142
	v_div_fmas_f32 v0, v0, v134, v143
	v_div_fixup_f32 v132, v0, v132, 1.0
	v_lshlrev_b32_e32 v0, 16, v135
	v_mul_f32_e32 v0, 0xbfb8aa3b, v0
	v_pk_mul_f32 v[142:143], v[56:57], v[132:133]
	v_exp_f32_e32 v132, v0
	v_and_b32_e32 v0, 0xffff0000, v135
	v_mul_f32_e32 v0, 0xbfb8aa3b, v0
	v_exp_f32_e32 v133, v0
	s_nop 0
	v_pk_add_f32 v[132:133], v[132:133], 1.0 op_sel_hi:[1,0]
	s_nop 0
	v_div_scale_f32 v0, s[28:29], v133, v133, 1.0
	v_rcp_f32_e32 v134, v0
	s_nop 0
	v_fma_f32 v135, -v0, v134, 1.0
	v_fmac_f32_e32 v134, v135, v134
	v_div_scale_f32 v135, vcc, 1.0, v133, 1.0
	v_mul_f32_e32 v144, v135, v134
	v_fma_f32 v145, -v0, v144, v135
	v_fmac_f32_e32 v144, v145, v134
	v_fma_f32 v0, -v0, v144, v135
	v_div_fmas_f32 v0, v0, v134, v144
	v_div_fixup_f32 v133, v0, v133, 1.0
	v_div_scale_f32 v0, s[28:29], v132, v132, 1.0
	v_rcp_f32_e32 v134, v0
	s_nop 0
	v_fma_f32 v135, -v0, v134, 1.0
	v_fmac_f32_e32 v134, v135, v134
	v_div_scale_f32 v135, vcc, 1.0, v132, 1.0
	v_mul_f32_e32 v144, v135, v134
	v_fma_f32 v145, -v0, v144, v135
	v_fmac_f32_e32 v144, v145, v134
	v_fma_f32 v0, -v0, v144, v135
	v_div_fmas_f32 v0, v0, v134, v144
	v_div_fixup_f32 v132, v0, v132, 1.0
	v_pk_mul_f32 v[144:145], v[58:59], v[132:133]
	v_cvt_pk_bf16_f32 v132, v138, v139
	v_cvt_pk_bf16_f32 v133, v140, v141
	v_cvt_pk_bf16_f32 v134, v142, v143
	v_cvt_pk_bf16_f32 v135, v144, v145
	global_store_dwordx4 v[136:137], v[132:135], off offset:256 sc0 sc1
	s_nop 1
	v_mad_i64_i32 v[132:133], s[28:29], v154, s76, v[150:151]
	v_lshl_add_u64 v[132:133], v[132:133], 0, s[30:31]
	v_lshl_add_u64 v[134:135], v[132:133], 0, v[2:3]
	global_load_dwordx4 v[144:147], v[134:135], off
	v_lshl_add_u64 v[132:133], v[132:133], 0, v[152:153]
	global_load_dwordx4 v[140:143], v[132:133], off
	v_mad_i64_i32 v[132:133], s[28:29], v148, s76, v[150:151]
	v_lshl_add_u64 v[132:133], v[132:133], 0, s[30:31]
	v_lshl_add_u64 v[134:135], v[132:133], 0, v[2:3]
	v_lshl_add_u64 v[132:133], v[132:133], 0, v[152:153]
	global_load_dwordx4 v[136:139], v[134:135], off
	s_waitcnt vmcnt(0)
	v_lshlrev_b32_e32 v0, 16, v144
	v_mul_f32_e32 v0, 0xbfb8aa3b, v0
	v_exp_f32_e32 v150, v0
	v_and_b32_e32 v0, 0xffff0000, v144
	v_mul_f32_e32 v0, 0xbfb8aa3b, v0
	v_exp_f32_e32 v151, v0
	global_load_dwordx4 v[132:135], v[132:133], off
	v_pk_add_f32 v[150:151], v[150:151], 1.0 op_sel_hi:[1,0]
	s_nop 0
	v_div_scale_f32 v0, s[28:29], v151, v151, 1.0
	v_rcp_f32_e32 v144, v0
	s_nop 0
	v_fma_f32 v149, -v0, v144, 1.0
	v_fmac_f32_e32 v144, v149, v144
	v_div_scale_f32 v149, vcc, 1.0, v151, 1.0
	v_mul_f32_e32 v152, v149, v144
	v_fma_f32 v153, -v0, v152, v149
	v_fmac_f32_e32 v152, v153, v144
	v_fma_f32 v0, -v0, v152, v149
	v_div_fmas_f32 v0, v0, v144, v152
	v_div_fixup_f32 v151, v0, v151, 1.0
	v_div_scale_f32 v0, s[28:29], v150, v150, 1.0
	v_rcp_f32_e32 v144, v0
	s_nop 0
	v_fma_f32 v149, -v0, v144, 1.0
	v_fmac_f32_e32 v144, v149, v144
	v_div_scale_f32 v149, vcc, 1.0, v150, 1.0
	v_mul_f32_e32 v152, v149, v144
	v_fma_f32 v153, -v0, v152, v149
	v_fmac_f32_e32 v152, v153, v144
	v_fma_f32 v0, -v0, v152, v149
	v_div_fmas_f32 v0, v0, v144, v152
	v_div_fixup_f32 v150, v0, v150, 1.0
	v_lshlrev_b32_e32 v0, 16, v145
	v_mul_f32_e32 v0, 0xbfb8aa3b, v0
	v_exp_f32_e32 v144, v0
	v_and_b32_e32 v0, 0xffff0000, v145
	v_mul_f32_e32 v0, 0xbfb8aa3b, v0
	v_exp_f32_e32 v145, v0
	v_pk_mul_f32 v[150:151], v[20:21], v[150:151]
	v_pk_add_f32 v[144:145], v[144:145], 1.0 op_sel_hi:[1,0]
	s_nop 0
	v_div_scale_f32 v0, s[28:29], v145, v145, 1.0
	v_rcp_f32_e32 v149, v0
	v_cvt_pk_bf16_f32 v150, v150, v151
	v_fma_f32 v152, -v0, v149, 1.0
	v_fmac_f32_e32 v149, v152, v149
	v_div_scale_f32 v152, vcc, 1.0, v145, 1.0
	v_mul_f32_e32 v153, v152, v149
	v_fma_f32 v156, -v0, v153, v152
	v_fmac_f32_e32 v153, v156, v149
	v_fma_f32 v0, -v0, v153, v152
	v_div_fmas_f32 v0, v0, v149, v153
	v_div_fixup_f32 v145, v0, v145, 1.0
	v_div_scale_f32 v0, s[28:29], v144, v144, 1.0
	v_rcp_f32_e32 v149, v0
	s_nop 0
	v_fma_f32 v152, -v0, v149, 1.0
	v_fmac_f32_e32 v149, v152, v149
	v_div_scale_f32 v152, vcc, 1.0, v144, 1.0
	v_mul_f32_e32 v153, v152, v149
	v_fma_f32 v156, -v0, v153, v152
	v_fmac_f32_e32 v153, v156, v149
	v_fma_f32 v0, -v0, v153, v152
	v_div_fmas_f32 v0, v0, v149, v153
	v_div_fixup_f32 v144, v0, v144, 1.0
	v_lshlrev_b32_e32 v0, 16, v146
	v_mul_f32_e32 v0, 0xbfb8aa3b, v0
	v_exp_f32_e32 v152, v0
	v_and_b32_e32 v0, 0xffff0000, v146
	v_mul_f32_e32 v0, 0xbfb8aa3b, v0
	v_exp_f32_e32 v153, v0
	v_pk_mul_f32 v[144:145], v[22:23], v[144:145]
	v_pk_add_f32 v[152:153], v[152:153], 1.0 op_sel_hi:[1,0]
	s_nop 0
	v_div_scale_f32 v0, s[28:29], v153, v153, 1.0
	v_rcp_f32_e32 v146, v0
	v_cvt_pk_bf16_f32 v151, v144, v145
	v_lshlrev_b64 v[144:145], 12, v[154:155]
	v_lshl_add_u64 v[144:145], s[10:11], 0, v[144:145]
	v_fma_f32 v149, -v0, v146, 1.0
	v_fmac_f32_e32 v146, v149, v146
	v_div_scale_f32 v149, vcc, 1.0, v153, 1.0
	v_mul_f32_e32 v156, v149, v146
	v_fma_f32 v157, -v0, v156, v149
	v_fmac_f32_e32 v156, v157, v146
	v_fma_f32 v0, -v0, v156, v149
	v_div_fmas_f32 v0, v0, v146, v156
	v_div_fixup_f32 v153, v0, v153, 1.0
	v_div_scale_f32 v0, s[28:29], v152, v152, 1.0
	v_rcp_f32_e32 v146, v0
	v_lshl_add_u64 v[144:145], v[144:145], 0, v[2:3]
	v_fma_f32 v149, -v0, v146, 1.0
	v_fmac_f32_e32 v146, v149, v146
	v_div_scale_f32 v149, vcc, 1.0, v152, 1.0
	v_mul_f32_e32 v156, v149, v146
	v_fma_f32 v157, -v0, v156, v149
	v_fmac_f32_e32 v156, v157, v146
	v_fma_f32 v0, -v0, v156, v149
	v_div_fmas_f32 v0, v0, v146, v156
	v_div_fixup_f32 v152, v0, v152, 1.0
	v_lshlrev_b32_e32 v0, 16, v147
; __device__ __forceinline__ unsigned pkh(float lo, float hi) { f32v2_t v; v.x = lo; v.y = hi; return __builtin_bit_cast(unsigned, __builtin_convertvector(v, bf16v2_t)); }
; __device__ __forceinline__ float bf_lo(unsigned w) { return __uint_as_float(w << 16); }
; __device__ __forceinline__ float bf_hi(unsigned w) { return __uint_as_float(w & 0xffff0000u); }
; __device__ __forceinline__ float sigmoidf_(float x) { return 1.0f / (1.0f + __expf(-x)); }
;     template <int MODE> __device__ __forceinline__ void run(const pg8::f32x4 (&acc)[2][2][4][2], const pg8::Unit& u, int wr, int wc, int fr, int fq) const {
;     ...
;                 if constexpr (MODE == 6) {
; #pragma unroll
;                     for (int q = 0; q < 4; ++q) { const int m = 2 * mp + (q >> 1), bj = q & 1; const int row = u.pm * 256 + ai * 128 + wr * 64 + m * 16 + fr, col = u.pn * 256 + bj * 128 + wc * 32 + 8 * fq;
;                         gpre[q] = *(const u32x4*)(proj + (size_t)row * NP + OFF_MG + 2 * DM + col); }
;                 }
; #pragma unroll
;                 for (int q = 0; q < 4; ++q) { const int m = 2 * mp + (q >> 1), bj = q & 1; const int row = u.pm * 256 + ai * 128 + wr * 64 + m * 16 + fr, col = u.pn * 256 + bj * 128 + wc * 32 + 8 * fq;
;                     const pg8::f32x4 t0 = acc[ai][bj][m][0], t1 = acc[ai][bj][m][1];
;                     float v[8] = {t0[0], t0[1], t0[2], t0[3], t1[0], t1[1], t1[2], t1[3]};
;                     if constexpr (MODE == 5) {
; #pragma unroll
;                         for (int e = 0; e < 8; ++e) { const float r = fmaxf(v[e], 0.f); v[e] = r * r; }
;                     }
;                     if constexpr (MODE == 6) { const u32x4 g = gpre[q];
;                         v[0] *= sigmoidf_(bf_lo(g.x)); v[1] *= sigmoidf_(bf_hi(g.x)); v[2] *= sigmoidf_(bf_lo(g.y)); v[3] *= sigmoidf_(bf_hi(g.y));
;                         v[4] *= sigmoidf_(bf_lo(g.z)); v[5] *= sigmoidf_(bf_hi(g.z)); v[6] *= sigmoidf_(bf_lo(g.w)); v[7] *= sigmoidf_(bf_hi(g.w)); }
;                     u32x4 w; w.x = pkh(v[0], v[1]); w.y = pkh(v[2], v[3]); w.z = pkh(v[4], v[5]); w.w = pkh(v[6], v[7]);
;                     *(u32x4*)(ob + (size_t)row * LDC + col) = w; }
	v_mul_f32_e32 v0, 0xbfb8aa3b, v0
	v_exp_f32_e32 v146, v0
	v_and_b32_e32 v0, 0xffff0000, v147
	v_mul_f32_e32 v0, 0xbfb8aa3b, v0
	v_exp_f32_e32 v147, v0
	v_pk_mul_f32 v[152:153], v[24:25], v[152:153]
	v_pk_add_f32 v[146:147], v[146:147], 1.0 op_sel_hi:[1,0]
	s_nop 0
	v_div_scale_f32 v0, s[28:29], v147, v147, 1.0
	v_rcp_f32_e32 v149, v0
	v_cvt_pk_bf16_f32 v152, v152, v153
	v_fma_f32 v156, -v0, v149, 1.0
	v_fmac_f32_e32 v149, v156, v149
	v_div_scale_f32 v156, vcc, 1.0, v147, 1.0
	v_mul_f32_e32 v157, v156, v149
	v_fma_f32 v158, -v0, v157, v156
	v_fmac_f32_e32 v157, v158, v149
	v_fma_f32 v0, -v0, v157, v156
	v_div_fmas_f32 v0, v0, v149, v157
	v_div_fixup_f32 v147, v0, v147, 1.0
	v_div_scale_f32 v0, s[28:29], v146, v146, 1.0
	v_rcp_f32_e32 v149, v0
	s_nop 0
	v_fma_f32 v156, -v0, v149, 1.0
	v_fmac_f32_e32 v149, v156, v149
	v_div_scale_f32 v156, vcc, 1.0, v146, 1.0
	v_mul_f32_e32 v157, v156, v149
	v_fma_f32 v158, -v0, v157, v156
	v_fmac_f32_e32 v157, v158, v149
	v_fma_f32 v0, -v0, v157, v156
	v_div_fmas_f32 v0, v0, v149, v157
	v_div_fixup_f32 v146, v0, v146, 1.0
	v_lshlrev_b32_e32 v0, 16, v140
	v_pk_mul_f32 v[146:147], v[26:27], v[146:147]
	v_mul_f32_e32 v0, 0xbfb8aa3b, v0
	v_cvt_pk_bf16_f32 v153, v146, v147
	v_exp_f32_e32 v146, v0
	v_and_b32_e32 v0, 0xffff0000, v140
	v_mul_f32_e32 v0, 0xbfb8aa3b, v0
	v_exp_f32_e32 v147, v0
	global_store_dwordx4 v[144:145], v[150:153], off sc0 sc1
	v_pk_add_f32 v[146:147], v[146:147], 1.0 op_sel_hi:[1,0]
	s_nop 0
	v_div_scale_f32 v0, s[28:29], v147, v147, 1.0
	v_rcp_f32_e32 v140, v0
	s_nop 0
	v_fma_f32 v149, -v0, v140, 1.0
	v_fmac_f32_e32 v140, v149, v140
	v_div_scale_f32 v149, vcc, 1.0, v147, 1.0
	v_mul_f32_e32 v150, v149, v140
	v_fma_f32 v151, -v0, v150, v149
	v_fmac_f32_e32 v150, v151, v140
	v_fma_f32 v0, -v0, v150, v149
	v_div_fmas_f32 v0, v0, v140, v150
	v_div_fixup_f32 v147, v0, v147, 1.0
	v_div_scale_f32 v0, s[28:29], v146, v146, 1.0
	v_rcp_f32_e32 v140, v0
	s_nop 0
	v_fma_f32 v149, -v0, v140, 1.0
	v_fmac_f32_e32 v140, v149, v140
	v_div_scale_f32 v149, vcc, 1.0, v146, 1.0
	v_mul_f32_e32 v150, v149, v140
	v_fma_f32 v151, -v0, v150, v149
	v_fmac_f32_e32 v150, v151, v140
	v_fma_f32 v0, -v0, v150, v149
	v_div_fmas_f32 v0, v0, v140, v150
	v_div_fixup_f32 v146, v0, v146, 1.0
	v_lshlrev_b32_e32 v0, 16, v141
	v_mul_f32_e32 v0, 0xbfb8aa3b, v0
	v_exp_f32_e32 v140, v0
	v_and_b32_e32 v0, 0xffff0000, v141
	v_mul_f32_e32 v0, 0xbfb8aa3b, v0
	v_exp_f32_e32 v141, v0
	v_pk_mul_f32 v[146:147], v[28:29], v[146:147]
	v_pk_add_f32 v[140:141], v[140:141], 1.0 op_sel_hi:[1,0]
	s_nop 0
	v_div_scale_f32 v0, s[28:29], v141, v141, 1.0
	v_rcp_f32_e32 v149, v0
	s_nop 0
	v_fma_f32 v150, -v0, v149, 1.0
	v_fmac_f32_e32 v149, v150, v149
	v_div_scale_f32 v150, vcc, 1.0, v141, 1.0
	v_mul_f32_e32 v151, v150, v149
	v_fma_f32 v152, -v0, v151, v150
	v_fmac_f32_e32 v151, v152, v149
	v_fma_f32 v0, -v0, v151, v150
	v_div_fmas_f32 v0, v0, v149, v151
	v_div_fixup_f32 v141, v0, v141, 1.0
	v_div_scale_f32 v0, s[28:29], v140, v140, 1.0
	v_rcp_f32_e32 v149, v0
	s_nop 0
	v_fma_f32 v150, -v0, v149, 1.0
	v_fmac_f32_e32 v149, v150, v149
	v_div_scale_f32 v150, vcc, 1.0, v140, 1.0
	v_mul_f32_e32 v151, v150, v149
	v_fma_f32 v152, -v0, v151, v150
	v_fmac_f32_e32 v151, v152, v149
	v_fma_f32 v0, -v0, v151, v150
	v_div_fmas_f32 v0, v0, v149, v151
	v_div_fixup_f32 v140, v0, v140, 1.0
	v_lshlrev_b32_e32 v0, 16, v142
	v_mul_f32_e32 v0, 0xbfb8aa3b, v0
	v_pk_mul_f32 v[150:151], v[30:31], v[140:141]
	v_exp_f32_e32 v140, v0
	v_and_b32_e32 v0, 0xffff0000, v142
	v_mul_f32_e32 v0, 0xbfb8aa3b, v0
	v_exp_f32_e32 v141, v0
	s_nop 0
	v_pk_add_f32 v[140:141], v[140:141], 1.0 op_sel_hi:[1,0]
	s_nop 0
	v_div_scale_f32 v0, s[28:29], v141, v141, 1.0
	v_rcp_f32_e32 v142, v0
	s_nop 0
	v_fma_f32 v149, -v0, v142, 1.0
	v_fmac_f32_e32 v142, v149, v142
	v_div_scale_f32 v149, vcc, 1.0, v141, 1.0
	v_mul_f32_e32 v152, v149, v142
	v_fma_f32 v153, -v0, v152, v149
	v_fmac_f32_e32 v152, v153, v142
	v_fma_f32 v0, -v0, v152, v149
	v_div_fmas_f32 v0, v0, v142, v152
	v_div_fixup_f32 v141, v0, v141, 1.0
	v_div_scale_f32 v0, s[28:29], v140, v140, 1.0
	v_rcp_f32_e32 v142, v0
	s_nop 0
	v_fma_f32 v149, -v0, v142, 1.0
	v_fmac_f32_e32 v142, v149, v142
	v_div_scale_f32 v149, vcc, 1.0, v140, 1.0
	v_mul_f32_e32 v152, v149, v142
	v_fma_f32 v153, -v0, v152, v149
	v_fmac_f32_e32 v152, v153, v142
	v_fma_f32 v0, -v0, v152, v149
	v_div_fmas_f32 v0, v0, v142, v152
	v_div_fixup_f32 v140, v0, v140, 1.0
	v_lshlrev_b32_e32 v0, 16, v143
	v_mul_f32_e32 v0, 0xbfb8aa3b, v0
	v_pk_mul_f32 v[152:153], v[32:33], v[140:141]
	v_exp_f32_e32 v140, v0
	v_and_b32_e32 v0, 0xffff0000, v143
	v_mul_f32_e32 v0, 0xbfb8aa3b, v0
	v_exp_f32_e32 v141, v0
	s_nop 0
	v_pk_add_f32 v[140:141], v[140:141], 1.0 op_sel_hi:[1,0]
	s_nop 0
	v_div_scale_f32 v0, s[28:29], v141, v141, 1.0
	v_rcp_f32_e32 v142, v0
	s_nop 0
	v_fma_f32 v143, -v0, v142, 1.0
	v_fmac_f32_e32 v142, v143, v142
	v_div_scale_f32 v143, vcc, 1.0, v141, 1.0
	v_mul_f32_e32 v149, v143, v142
	v_fma_f32 v154, -v0, v149, v143
	v_fmac_f32_e32 v149, v154, v142
	v_fma_f32 v0, -v0, v149, v143
	v_div_fmas_f32 v0, v0, v142, v149
	v_div_fixup_f32 v141, v0, v141, 1.0
	v_div_scale_f32 v0, s[28:29], v140, v140, 1.0
	v_rcp_f32_e32 v142, v0
	s_nop 0
	v_fma_f32 v143, -v0, v142, 1.0
	v_fmac_f32_e32 v142, v143, v142
	v_div_scale_f32 v143, vcc, 1.0, v140, 1.0
	v_mul_f32_e32 v149, v143, v142
	v_fma_f32 v154, -v0, v149, v143
	v_fmac_f32_e32 v149, v154, v142
	v_fma_f32 v0, -v0, v149, v143
	v_div_fmas_f32 v0, v0, v142, v149
	v_div_fixup_f32 v140, v0, v140, 1.0
	v_pk_mul_f32 v[154:155], v[34:35], v[140:141]
	v_lshlrev_b32_e32 v0, 16, v136
	v_cvt_pk_bf16_f32 v140, v146, v147
	v_cvt_pk_bf16_f32 v141, v150, v151
; __device__ __forceinline__ unsigned pkh(float lo, float hi) { f32v2_t v; v.x = lo; v.y = hi; return __builtin_bit_cast(unsigned, __builtin_convertvector(v, bf16v2_t)); }
; __device__ __forceinline__ float bf_lo(unsigned w) { return __uint_as_float(w << 16); }
; __device__ __forceinline__ float bf_hi(unsigned w) { return __uint_as_float(w & 0xffff0000u); }
; __device__ __forceinline__ float sigmoidf_(float x) { return 1.0f / (1.0f + __expf(-x)); }
;     template <int MODE> __device__ __forceinline__ void run(const pg8::f32x4 (&acc)[2][2][4][2], const pg8::Unit& u, int wr, int wc, int fr, int fq) const {
;     ...
;                 if constexpr (MODE == 6) {
; #pragma unroll
;                     for (int q = 0; q < 4; ++q) { const int m = 2 * mp + (q >> 1), bj = q & 1; const int row = u.pm * 256 + ai * 128 + wr * 64 + m * 16 + fr, col = u.pn * 256 + bj * 128 + wc * 32 + 8 * fq;
;                         gpre[q] = *(const u32x4*)(proj + (size_t)row * NP + OFF_MG + 2 * DM + col); }
;                 }
; #pragma unroll
;                 for (int q = 0; q < 4; ++q) { const int m = 2 * mp + (q >> 1), bj = q & 1; const int row = u.pm * 256 + ai * 128 + wr * 64 + m * 16 + fr, col = u.pn * 256 + bj * 128 + wc * 32 + 8 * fq;
;                     const pg8::f32x4 t0 = acc[ai][bj][m][0], t1 = acc[ai][bj][m][1];
;                     float v[8] = {t0[0], t0[1], t0[2], t0[3], t1[0], t1[1], t1[2], t1[3]};
;                     if constexpr (MODE == 5) {
; #pragma unroll
;                         for (int e = 0; e < 8; ++e) { const float r = fmaxf(v[e], 0.f); v[e] = r * r; }
;                     }
;                     if constexpr (MODE == 6) { const u32x4 g = gpre[q];
;                         v[0] *= sigmoidf_(bf_lo(g.x)); v[1] *= sigmoidf_(bf_hi(g.x)); v[2] *= sigmoidf_(bf_lo(g.y)); v[3] *= sigmoidf_(bf_hi(g.y));
;                         v[4] *= sigmoidf_(bf_lo(g.z)); v[5] *= sigmoidf_(bf_hi(g.z)); v[6] *= sigmoidf_(bf_lo(g.w)); v[7] *= sigmoidf_(bf_hi(g.w)); }
;                     u32x4 w; w.x = pkh(v[0], v[1]); w.y = pkh(v[2], v[3]); w.z = pkh(v[4], v[5]); w.w = pkh(v[6], v[7]);
;                     *(u32x4*)(ob + (size_t)row * LDC + col) = w; }
	v_cvt_pk_bf16_f32 v142, v152, v153
	v_cvt_pk_bf16_f32 v143, v154, v155
	v_mul_f32_e32 v0, 0xbfb8aa3b, v0
	global_store_dwordx4 v[144:145], v[140:143], off offset:256 sc0 sc1
	v_ashrrev_i32_e32 v149, 31, v148
	s_nop 0
	v_exp_f32_e32 v140, v0
	v_and_b32_e32 v0, 0xffff0000, v136
	v_mul_f32_e32 v0, 0xbfb8aa3b, v0
	v_exp_f32_e32 v141, v0
	s_nop 0
	v_pk_add_f32 v[140:141], v[140:141], 1.0 op_sel_hi:[1,0]
	s_nop 0
	v_div_scale_f32 v0, s[28:29], v141, v141, 1.0
	v_rcp_f32_e32 v136, v0
	s_nop 0
	v_fma_f32 v142, -v0, v136, 1.0
	v_fmac_f32_e32 v136, v142, v136
	v_div_scale_f32 v142, vcc, 1.0, v141, 1.0
	v_mul_f32_e32 v143, v142, v136
	v_fma_f32 v144, -v0, v143, v142
	v_fmac_f32_e32 v143, v144, v136
	v_fma_f32 v0, -v0, v143, v142
	v_div_fmas_f32 v0, v0, v136, v143
	v_div_fixup_f32 v141, v0, v141, 1.0
	v_div_scale_f32 v0, s[28:29], v140, v140, 1.0
	v_rcp_f32_e32 v136, v0
	s_nop 0
	v_fma_f32 v142, -v0, v136, 1.0
	v_fmac_f32_e32 v136, v142, v136
	v_div_scale_f32 v142, vcc, 1.0, v140, 1.0
	v_mul_f32_e32 v143, v142, v136
	v_fma_f32 v144, -v0, v143, v142
	v_fmac_f32_e32 v143, v144, v136
	v_fma_f32 v0, -v0, v143, v142
	v_div_fmas_f32 v0, v0, v136, v143
	v_div_fixup_f32 v140, v0, v140, 1.0
	v_lshlrev_b32_e32 v0, 16, v137
	v_mul_f32_e32 v0, 0xbfb8aa3b, v0
	v_exp_f32_e32 v136, v0
	v_and_b32_e32 v0, 0xffff0000, v137
	v_mul_f32_e32 v0, 0xbfb8aa3b, v0
	v_exp_f32_e32 v137, v0
	v_pk_mul_f32 v[140:141], v[4:5], v[140:141]
	v_pk_add_f32 v[136:137], v[136:137], 1.0 op_sel_hi:[1,0]
	s_nop 0
	v_div_scale_f32 v0, s[28:29], v137, v137, 1.0
	v_rcp_f32_e32 v142, v0
	s_nop 0
	v_fma_f32 v143, -v0, v142, 1.0
	v_fmac_f32_e32 v142, v143, v142
	v_div_scale_f32 v143, vcc, 1.0, v137, 1.0
	v_mul_f32_e32 v144, v143, v142
	v_fma_f32 v145, -v0, v144, v143
	v_fmac_f32_e32 v144, v145, v142
	v_fma_f32 v0, -v0, v144, v143
	v_div_fmas_f32 v0, v0, v142, v144
	v_div_fixup_f32 v137, v0, v137, 1.0
	v_div_scale_f32 v0, s[28:29], v136, v136, 1.0
	v_rcp_f32_e32 v142, v0
	s_nop 0
	v_fma_f32 v143, -v0, v142, 1.0
	v_fmac_f32_e32 v142, v143, v142
	v_div_scale_f32 v143, vcc, 1.0, v136, 1.0
	v_mul_f32_e32 v144, v143, v142
	v_fma_f32 v145, -v0, v144, v143
	v_fmac_f32_e32 v144, v145, v142
	v_fma_f32 v0, -v0, v144, v143
	v_div_fmas_f32 v0, v0, v142, v144
	v_div_fixup_f32 v136, v0, v136, 1.0
	v_lshlrev_b32_e32 v0, 16, v138
	v_mul_f32_e32 v0, 0xbfb8aa3b, v0
	v_pk_mul_f32 v[142:143], v[6:7], v[136:137]
	v_exp_f32_e32 v136, v0
	v_and_b32_e32 v0, 0xffff0000, v138
	v_mul_f32_e32 v0, 0xbfb8aa3b, v0
	v_exp_f32_e32 v137, v0
	s_nop 0
	v_pk_add_f32 v[136:137], v[136:137], 1.0 op_sel_hi:[1,0]
	s_nop 0
	v_div_scale_f32 v0, s[28:29], v137, v137, 1.0
	v_rcp_f32_e32 v138, v0
	s_nop 0
	v_fma_f32 v144, -v0, v138, 1.0
	v_fmac_f32_e32 v138, v144, v138
	v_div_scale_f32 v144, vcc, 1.0, v137, 1.0
	v_mul_f32_e32 v145, v144, v138
	v_fma_f32 v146, -v0, v145, v144
	v_fmac_f32_e32 v145, v146, v138
	v_fma_f32 v0, -v0, v145, v144
	v_div_fmas_f32 v0, v0, v138, v145
	v_div_fixup_f32 v137, v0, v137, 1.0
	v_div_scale_f32 v0, s[28:29], v136, v136, 1.0
	v_rcp_f32_e32 v138, v0
	s_nop 0
	v_fma_f32 v144, -v0, v138, 1.0
	v_fmac_f32_e32 v138, v144, v138
	v_div_scale_f32 v144, vcc, 1.0, v136, 1.0
	v_mul_f32_e32 v145, v144, v138
	v_fma_f32 v146, -v0, v145, v144
	v_fmac_f32_e32 v145, v146, v138
	v_fma_f32 v0, -v0, v145, v144
	v_div_fmas_f32 v0, v0, v138, v145
	v_div_fixup_f32 v136, v0, v136, 1.0
	v_lshlrev_b32_e32 v0, 16, v139
	v_mul_f32_e32 v0, 0xbfb8aa3b, v0
	v_pk_mul_f32 v[144:145], v[8:9], v[136:137]
	v_exp_f32_e32 v136, v0
	v_and_b32_e32 v0, 0xffff0000, v139
	v_mul_f32_e32 v0, 0xbfb8aa3b, v0
	v_exp_f32_e32 v137, v0
	s_nop 0
	v_pk_add_f32 v[136:137], v[136:137], 1.0 op_sel_hi:[1,0]
	s_nop 0
	v_div_scale_f32 v0, s[28:29], v137, v137, 1.0
	v_rcp_f32_e32 v138, v0
	s_nop 0
	v_fma_f32 v139, -v0, v138, 1.0
	v_fmac_f32_e32 v138, v139, v138
	v_div_scale_f32 v139, vcc, 1.0, v137, 1.0
	v_mul_f32_e32 v146, v139, v138
	v_fma_f32 v147, -v0, v146, v139
	v_fmac_f32_e32 v146, v147, v138
	v_fma_f32 v0, -v0, v146, v139
	v_div_fmas_f32 v0, v0, v138, v146
	v_div_fixup_f32 v137, v0, v137, 1.0
	v_div_scale_f32 v0, s[28:29], v136, v136, 1.0
	v_rcp_f32_e32 v138, v0
	s_nop 0
	v_fma_f32 v139, -v0, v138, 1.0
	v_fmac_f32_e32 v138, v139, v138
	v_div_scale_f32 v139, vcc, 1.0, v136, 1.0
	v_mul_f32_e32 v146, v139, v138
	v_fma_f32 v147, -v0, v146, v139
	v_fmac_f32_e32 v146, v147, v138
	v_fma_f32 v0, -v0, v146, v139
	v_div_fmas_f32 v0, v0, v138, v146
	v_div_fixup_f32 v136, v0, v136, 1.0
	v_pk_mul_f32 v[146:147], v[10:11], v[136:137]
	v_cvt_pk_bf16_f32 v136, v140, v141
	v_lshlrev_b64 v[140:141], 12, v[148:149]
	v_lshl_add_u64 v[140:141], s[10:11], 0, v[140:141]
	s_waitcnt vmcnt(0)
; __device__ __forceinline__ unsigned pkh(float lo, float hi) { f32v2_t v; v.x = lo; v.y = hi; return __builtin_bit_cast(unsigned, __builtin_convertvector(v, bf16v2_t)); }
; __device__ __forceinline__ float bf_lo(unsigned w) { return __uint_as_float(w << 16); }
; __device__ __forceinline__ float bf_hi(unsigned w) { return __uint_as_float(w & 0xffff0000u); }
; __device__ __forceinline__ float sigmoidf_(float x) { return 1.0f / (1.0f + __expf(-x)); }
;     template <int MODE> __device__ __forceinline__ void run(const pg8::f32x4 (&acc)[2][2][4][2], const pg8::Unit& u, int wr, int wc, int fr, int fq) const {
;     ...
;                 if constexpr (MODE == 6) {
; #pragma unroll
;                     for (int q = 0; q < 4; ++q) { const int m = 2 * mp + (q >> 1), bj = q & 1; const int row = u.pm * 256 + ai * 128 + wr * 64 + m * 16 + fr, col = u.pn * 256 + bj * 128 + wc * 32 + 8 * fq;
;                         gpre[q] = *(const u32x4*)(proj + (size_t)row * NP + OFF_MG + 2 * DM + col); }
;                 }
; #pragma unroll
;                 for (int q = 0; q < 4; ++q) { const int m = 2 * mp + (q >> 1), bj = q & 1; const int row = u.pm * 256 + ai * 128 + wr * 64 + m * 16 + fr, col = u.pn * 256 + bj * 128 + wc * 32 + 8 * fq;
;                     const pg8::f32x4 t0 = acc[ai][bj][m][0], t1 = acc[ai][bj][m][1];
;                     float v[8] = {t0[0], t0[1], t0[2], t0[3], t1[0], t1[1], t1[2], t1[3]};
;                     if constexpr (MODE == 5) {
; #pragma unroll
;                         for (int e = 0; e < 8; ++e) { const float r = fmaxf(v[e], 0.f); v[e] = r * r; }
;                     }
;                     if constexpr (MODE == 6) { const u32x4 g = gpre[q];
;                         v[0] *= sigmoidf_(bf_lo(g.x)); v[1] *= sigmoidf_(bf_hi(g.x)); v[2] *= sigmoidf_(bf_lo(g.y)); v[3] *= sigmoidf_(bf_hi(g.y));
;                         v[4] *= sigmoidf_(bf_lo(g.z)); v[5] *= sigmoidf_(bf_hi(g.z)); v[6] *= sigmoidf_(bf_lo(g.w)); v[7] *= sigmoidf_(bf_hi(g.w)); }
;                     u32x4 w; w.x = pkh(v[0], v[1]); w.y = pkh(v[2], v[3]); w.z = pkh(v[4], v[5]); w.w = pkh(v[6], v[7]);
;                     *(u32x4*)(ob + (size_t)row * LDC + col) = w; }
	v_lshlrev_b32_e32 v0, 16, v132
	v_cvt_pk_bf16_f32 v137, v142, v143
	v_cvt_pk_bf16_f32 v138, v144, v145
	v_cvt_pk_bf16_f32 v139, v146, v147
	v_lshl_add_u64 v[2:3], v[140:141], 0, v[2:3]
	v_mul_f32_e32 v0, 0xbfb8aa3b, v0
	global_store_dwordx4 v[2:3], v[136:139], off sc0 sc1
	s_nop 1
	v_exp_f32_e32 v136, v0
	v_and_b32_e32 v0, 0xffff0000, v132
	v_mul_f32_e32 v0, 0xbfb8aa3b, v0
	v_exp_f32_e32 v137, v0
	s_nop 0
	v_pk_add_f32 v[136:137], v[136:137], 1.0 op_sel_hi:[1,0]
	s_nop 0
	v_div_scale_f32 v0, s[28:29], v137, v137, 1.0
	v_rcp_f32_e32 v132, v0
	s_nop 0
	v_fma_f32 v138, -v0, v132, 1.0
	v_fmac_f32_e32 v132, v138, v132
	v_div_scale_f32 v138, vcc, 1.0, v137, 1.0
	v_mul_f32_e32 v139, v138, v132
	v_fma_f32 v140, -v0, v139, v138
	v_fmac_f32_e32 v139, v140, v132
	v_fma_f32 v0, -v0, v139, v138
	v_div_fmas_f32 v0, v0, v132, v139
	v_div_fixup_f32 v137, v0, v137, 1.0
	v_div_scale_f32 v0, s[28:29], v136, v136, 1.0
	v_rcp_f32_e32 v132, v0
	s_nop 0
	v_fma_f32 v138, -v0, v132, 1.0
	v_fmac_f32_e32 v132, v138, v132
	v_div_scale_f32 v138, vcc, 1.0, v136, 1.0
	v_mul_f32_e32 v139, v138, v132
	v_fma_f32 v140, -v0, v139, v138
	v_fmac_f32_e32 v139, v140, v132
	v_fma_f32 v0, -v0, v139, v138
	v_div_fmas_f32 v0, v0, v132, v139
	v_div_fixup_f32 v136, v0, v136, 1.0
	v_lshlrev_b32_e32 v0, 16, v133
	v_mul_f32_e32 v0, 0xbfb8aa3b, v0
	v_exp_f32_e32 v132, v0
	v_and_b32_e32 v0, 0xffff0000, v133
	v_mul_f32_e32 v0, 0xbfb8aa3b, v0
	v_exp_f32_e32 v133, v0
	v_pk_mul_f32 v[136:137], v[12:13], v[136:137]
	v_pk_add_f32 v[132:133], v[132:133], 1.0 op_sel_hi:[1,0]
	s_nop 0
	v_div_scale_f32 v0, s[28:29], v133, v133, 1.0
	v_rcp_f32_e32 v138, v0
	s_nop 0
	v_fma_f32 v139, -v0, v138, 1.0
	v_fmac_f32_e32 v138, v139, v138
	v_div_scale_f32 v139, vcc, 1.0, v133, 1.0
	v_mul_f32_e32 v140, v139, v138
	v_fma_f32 v141, -v0, v140, v139
	v_fmac_f32_e32 v140, v141, v138
	v_fma_f32 v0, -v0, v140, v139
	v_div_fmas_f32 v0, v0, v138, v140
	v_div_fixup_f32 v133, v0, v133, 1.0
	v_div_scale_f32 v0, s[28:29], v132, v132, 1.0
	v_rcp_f32_e32 v138, v0
	s_nop 0
	v_fma_f32 v139, -v0, v138, 1.0
	v_fmac_f32_e32 v138, v139, v138
	v_div_scale_f32 v139, vcc, 1.0, v132, 1.0
	v_mul_f32_e32 v140, v139, v138
	v_fma_f32 v141, -v0, v140, v139
	v_fmac_f32_e32 v140, v141, v138
	v_fma_f32 v0, -v0, v140, v139
	v_div_fmas_f32 v0, v0, v138, v140
	v_div_fixup_f32 v132, v0, v132, 1.0
	v_lshlrev_b32_e32 v0, 16, v134
	v_mul_f32_e32 v0, 0xbfb8aa3b, v0
	v_pk_mul_f32 v[138:139], v[14:15], v[132:133]
	v_exp_f32_e32 v132, v0
	v_and_b32_e32 v0, 0xffff0000, v134
	v_mul_f32_e32 v0, 0xbfb8aa3b, v0
	v_exp_f32_e32 v133, v0
	s_nop 0
	v_pk_add_f32 v[132:133], v[132:133], 1.0 op_sel_hi:[1,0]
	s_nop 0
	v_div_scale_f32 v0, s[28:29], v133, v133, 1.0
	v_rcp_f32_e32 v134, v0
	s_nop 0
	v_fma_f32 v140, -v0, v134, 1.0
	v_fmac_f32_e32 v134, v140, v134
	v_div_scale_f32 v140, vcc, 1.0, v133, 1.0
	v_mul_f32_e32 v141, v140, v134
	v_fma_f32 v142, -v0, v141, v140
	v_fmac_f32_e32 v141, v142, v134
	v_fma_f32 v0, -v0, v141, v140
	v_div_fmas_f32 v0, v0, v134, v141
	v_div_fixup_f32 v133, v0, v133, 1.0
	v_div_scale_f32 v0, s[28:29], v132, v132, 1.0
	v_rcp_f32_e32 v134, v0
	s_nop 0
	v_fma_f32 v140, -v0, v134, 1.0
	v_fmac_f32_e32 v134, v140, v134
	v_div_scale_f32 v140, vcc, 1.0, v132, 1.0
	v_mul_f32_e32 v141, v140, v134
	v_fma_f32 v142, -v0, v141, v140
	v_fmac_f32_e32 v141, v142, v134
	v_fma_f32 v0, -v0, v141, v140
	v_div_fmas_f32 v0, v0, v134, v141
	v_div_fixup_f32 v132, v0, v132, 1.0
	v_lshlrev_b32_e32 v0, 16, v135
	v_mul_f32_e32 v0, 0xbfb8aa3b, v0
	v_pk_mul_f32 v[140:141], v[16:17], v[132:133]
	v_exp_f32_e32 v132, v0
	v_and_b32_e32 v0, 0xffff0000, v135
	v_mul_f32_e32 v0, 0xbfb8aa3b, v0
	v_exp_f32_e32 v133, v0
	s_nop 0
	v_pk_add_f32 v[132:133], v[132:133], 1.0 op_sel_hi:[1,0]
	s_nop 0
	v_div_scale_f32 v0, s[28:29], v133, v133, 1.0
	v_rcp_f32_e32 v134, v0
	s_nop 0
	v_fma_f32 v135, -v0, v134, 1.0
	v_fmac_f32_e32 v134, v135, v134
	v_div_scale_f32 v135, vcc, 1.0, v133, 1.0
	v_mul_f32_e32 v142, v135, v134
	v_fma_f32 v143, -v0, v142, v135
	v_fmac_f32_e32 v142, v143, v134
	v_fma_f32 v0, -v0, v142, v135
	v_div_fmas_f32 v0, v0, v134, v142
	v_div_fixup_f32 v133, v0, v133, 1.0
	v_div_scale_f32 v0, s[28:29], v132, v132, 1.0
	v_rcp_f32_e32 v134, v0
	s_nop 0
	v_fma_f32 v135, -v0, v134, 1.0
	v_fmac_f32_e32 v134, v135, v134
	v_div_scale_f32 v135, vcc, 1.0, v132, 1.0
	v_mul_f32_e32 v142, v135, v134
	v_fma_f32 v143, -v0, v142, v135
	v_fmac_f32_e32 v142, v143, v134
	v_fma_f32 v0, -v0, v142, v135
	v_div_fmas_f32 v0, v0, v134, v142
	v_div_fixup_f32 v132, v0, v132, 1.0
	v_pk_mul_f32 v[142:143], v[18:19], v[132:133]
	v_cvt_pk_bf16_f32 v132, v136, v137
	v_cvt_pk_bf16_f32 v133, v138, v139
	v_cvt_pk_bf16_f32 v134, v140, v141
	v_cvt_pk_bf16_f32 v135, v142, v143
	global_store_dwordx4 v[2:3], v[132:135], off offset:256 sc0 sc1
	s_cbranch_execz .LBB0_74
